# residual epilogues (P8,P10,P12,P15): 7 of 8 second-half residual loads issued before the first-half wait (fresh VGPRs), so they no longer queue behind the first half's stores
# baseline (speedup 1.0000x reference)
.LBB0_1029:
	s_ashr_i32 s39, s38, 31
	s_lshl_b64 s[38:39], s[38:39], 8
	s_lshl_b32 s36, s36, 8
	v_mov_b32_e32 v173, s39
	v_or_b32_e32 v172, s38, v160
	v_add_u32_e32 v174, s36, v161
	v_lshlrev_b64 v[202:203], 1, v[172:173]
	v_ashrrev_i32_e32 v175, 31, v174
	v_lshl_add_u64 v[176:177], s[82:83], 0, v[202:203]
	v_lshlrev_b64 v[204:205], 11, v[174:175]
	v_lshl_add_u64 v[128:129], v[176:177], 0, v[204:205]
	global_load_dwordx4 v[194:197], v[128:129], off
	global_load_dwordx4 v[198:201], v[128:129], off offset:256
	v_or_b32_e32 v128, 16, v174
	v_or_b32_e32 v130, 32, v174
	v_or_b32_e32 v132, 48, v174
	v_ashrrev_i32_e32 v129, 31, v128
	v_ashrrev_i32_e32 v131, 31, v130
	v_ashrrev_i32_e32 v133, 31, v132
	v_lshlrev_b64 v[182:183], 11, v[128:129]
	v_lshlrev_b64 v[180:181], 11, v[130:131]
	v_lshlrev_b64 v[178:179], 11, v[132:133]
	v_lshl_add_u64 v[128:129], v[176:177], 0, v[182:183]
	v_lshl_add_u64 v[130:131], v[176:177], 0, v[180:181]
	v_lshl_add_u64 v[206:207], v[176:177], 0, v[178:179]
	global_load_dwordx4 v[148:151], v[128:129], off
	global_load_dwordx4 v[144:147], v[128:129], off offset:256
	global_load_dwordx4 v[140:143], v[130:131], off
	global_load_dwordx4 v[136:139], v[130:131], off offset:256
	global_load_dwordx4 v[132:135], v[206:207], off
	s_nop 0
	global_load_dwordx4 v[128:131], v[206:207], off offset:256
	v_and_b32_e32 v193, 64, v192
	v_xor_b32_e32 v175, 16, v192
	v_add_u32_e32 v193, 64, v193
	v_xor_b32_e32 v206, 32, v192
	v_cmp_lt_i32_e32 vcc, v175, v193
	v_add_u32_e32 v218, 0x80, v174
	v_ashrrev_i32_e32 v219, 31, v218
	v_lshlrev_b64 v[218:219], 11, v[218:219]
	v_lshl_add_u64 v[218:219], v[176:177], 0, v[218:219]
	global_load_dwordx4 v[214:217], v[218:219], off
	global_load_dwordx4 v[218:221], v[218:219], off offset:256
	v_add_u32_e32 v226, 0x90, v174
	v_ashrrev_i32_e32 v227, 31, v226
	v_lshlrev_b64 v[226:227], 11, v[226:227]
	v_lshl_add_u64 v[226:227], v[176:177], 0, v[226:227]
	global_load_dwordx4 v[222:225], v[226:227], off
	global_load_dwordx4 v[226:229], v[226:227], off offset:256
	v_add_u32_e32 v234, 0xa0, v174
	v_ashrrev_i32_e32 v235, 31, v234
	v_lshlrev_b64 v[234:235], 11, v[234:235]
	v_lshl_add_u64 v[234:235], v[176:177], 0, v[234:235]
	global_load_dwordx4 v[230:233], v[234:235], off
	global_load_dwordx4 v[234:237], v[234:235], off offset:256
	v_add_u32_e32 v238, 0xb0, v174
	v_ashrrev_i32_e32 v239, 31, v238
	v_lshlrev_b64 v[238:239], 11, v[238:239]
	v_lshl_add_u64 v[238:239], v[176:177], 0, v[238:239]
	global_load_dwordx4 v[238:241], v[238:239], off
	s_waitcnt vmcnt(7)
	v_and_b32_e32 v207, 0xffff0000, v194
	v_cndmask_b32_e32 v175, v192, v175, vcc
	v_cmp_lt_i32_e32 vcc, v206, v193
	v_lshlrev_b32_e32 v193, 2, v175
	v_lshlrev_b32_e32 v208, 16, v196
	v_cndmask_b32_e32 v206, v192, v206, vcc
	v_lshlrev_b32_e32 v175, 2, v206
	v_lshlrev_b32_e32 v206, 16, v194
	v_lshlrev_b32_e32 v194, 16, v195
	v_and_b32_e32 v195, 0xffff0000, v195
	v_and_b32_e32 v209, 0xffff0000, v196
	v_lshlrev_b32_e32 v196, 16, v197
	v_and_b32_e32 v197, 0xffff0000, v197
	v_lshlrev_b32_e32 v210, 16, v198
	v_and_b32_e32 v211, 0xffff0000, v198
	v_lshlrev_b32_e32 v198, 16, v199
	v_and_b32_e32 v199, 0xffff0000, v199
	v_lshlrev_b32_e32 v212, 16, v200
	v_and_b32_e32 v213, 0xffff0000, v200
	v_lshlrev_b32_e32 v200, 16, v201
	v_and_b32_e32 v201, 0xffff0000, v201
	v_pk_add_f32 v[126:127], v[126:127], v[194:195]
	v_pk_add_f32 v[124:125], v[124:125], v[206:207]
	v_pk_add_f32 v[122:123], v[122:123], v[196:197]
	v_pk_add_f32 v[120:121], v[120:121], v[208:209]
	v_pk_add_f32 v[118:119], v[118:119], v[198:199]
	v_pk_add_f32 v[116:117], v[116:117], v[210:211]
	v_pk_add_f32 v[194:195], v[114:115], v[200:201]
	v_pk_add_f32 v[196:197], v[112:113], v[212:213]
	v_mul_f32_e32 v198, v125, v125
	v_mul_f32_e32 v199, v127, v127
	v_mul_f32_e32 v200, v121, v121
	v_mul_f32_e32 v201, v123, v123
	v_cvt_pk_bf16_f32 v114, v120, v121
	v_cvt_pk_bf16_f32 v115, v122, v123
	v_mul_f32_e32 v121, v117, v117
	v_mul_f32_e32 v123, v119, v119
	v_cvt_pk_bf16_f32 v112, v124, v125
	v_mul_f32_e32 v125, v197, v197
	v_fmac_f32_e32 v198, v124, v124
	v_fmac_f32_e32 v199, v126, v126
	v_fmac_f32_e32 v121, v116, v116
	v_fmac_f32_e32 v123, v118, v118
	v_cvt_pk_bf16_f32 v113, v126, v127
	v_mul_f32_e32 v127, v195, v195
	v_fmac_f32_e32 v200, v120, v120
	v_fmac_f32_e32 v125, v196, v196
	v_add_f32_e32 v120, v198, v199
	v_add_f32_e32 v121, v121, v123
	v_fmac_f32_e32 v201, v122, v122
	v_fmac_f32_e32 v127, v194, v194
	v_add_f32_e32 v120, v200, v120
	v_add_f32_e32 v121, v125, v121
	v_add_f32_e32 v120, v201, v120
	v_add_f32_e32 v121, v127, v121
	v_add_f32_e32 v122, v120, v121
	ds_bpermute_b32 v123, v193, v122
	v_lshl_add_u64 v[120:121], s[82:83], 0, v[204:205]
	v_lshl_add_u64 v[120:121], v[120:121], 0, v[202:203]
	global_store_dwordx4 v[120:121], v[112:115], off
	s_waitcnt lgkmcnt(0)
	s_nop 0
	v_add_f32_e32 v112, v122, v123
	ds_bpermute_b32 v113, v175, v112
	v_cvt_pk_bf16_f32 v114, v116, v117
	v_cvt_pk_bf16_f32 v115, v118, v119
	v_cvt_pk_bf16_f32 v116, v196, v197
	v_cvt_pk_bf16_f32 v117, v194, v195
	global_store_dwordx4 v[120:121], v[114:117], off offset:256
	s_and_saveexec_b64 s[38:39], s[4:5]
	s_cbranch_execz .LBB0_1031
	s_waitcnt lgkmcnt(0)
	v_add_f32_e32 v112, v112, v113
	ds_write_b32 v187, v112

.LBB0_1037:
	s_or_b64 exec, exec, s[38:39]
	v_add_u32_e32 v64, 0x80, v174
	s_waitcnt lgkmcnt(0)
	v_ashrrev_i32_e32 v65, 31, v64
	v_lshlrev_b64 v[102:103], 11, v[64:65]
	v_lshl_add_u64 v[64:65], v[176:177], 0, v[102:103]
	v_add_u32_e32 v64, 0x90, v174
	v_add_u32_e32 v66, 0xa0, v174
	v_add_u32_e32 v68, 0xb0, v174
	v_ashrrev_i32_e32 v65, 31, v64
	v_ashrrev_i32_e32 v67, 31, v66
	v_ashrrev_i32_e32 v69, 31, v68
	v_lshlrev_b64 v[92:93], 11, v[64:65]
	v_lshlrev_b64 v[90:91], 11, v[66:67]
	v_lshlrev_b64 v[88:89], 11, v[68:69]
	v_lshl_add_u64 v[64:65], v[176:177], 0, v[92:93]
	v_lshl_add_u64 v[66:67], v[176:177], 0, v[90:91]
	v_lshl_add_u64 v[104:105], v[176:177], 0, v[88:89]
	s_nop 0
	global_load_dwordx4 v[64:67], v[104:105], off offset:256
	s_waitcnt vmcnt(15)
	v_lshlrev_b32_e32 v104, 16, v214
	v_and_b32_e32 v105, 0xffff0000, v214
	v_lshlrev_b32_e32 v214, 16, v215
	v_and_b32_e32 v215, 0xffff0000, v215
	v_lshlrev_b32_e32 v106, 16, v216
	v_and_b32_e32 v107, 0xffff0000, v216
	v_lshlrev_b32_e32 v216, 16, v217
	v_and_b32_e32 v217, 0xffff0000, v217
	s_waitcnt vmcnt(14)
	v_lshlrev_b32_e32 v108, 16, v218
	v_and_b32_e32 v109, 0xffff0000, v218
	v_lshlrev_b32_e32 v218, 16, v219
	v_and_b32_e32 v219, 0xffff0000, v219
	v_lshlrev_b32_e32 v110, 16, v220
	v_and_b32_e32 v111, 0xffff0000, v220
	v_lshlrev_b32_e32 v220, 16, v221
	v_and_b32_e32 v221, 0xffff0000, v221
	v_pk_add_f32 v[62:63], v[62:63], v[214:215]
	v_pk_add_f32 v[60:61], v[60:61], v[104:105]
	v_pk_add_f32 v[58:59], v[58:59], v[216:217]
	v_pk_add_f32 v[56:57], v[56:57], v[106:107]
	v_pk_add_f32 v[54:55], v[54:55], v[218:219]
	v_pk_add_f32 v[52:53], v[52:53], v[108:109]
	v_pk_add_f32 v[214:215], v[50:51], v[220:221]
	v_pk_add_f32 v[216:217], v[48:49], v[110:111]
	v_mul_f32_e32 v218, v61, v61
	v_mul_f32_e32 v219, v63, v63
	v_mul_f32_e32 v220, v57, v57
	v_mul_f32_e32 v221, v59, v59
	v_cvt_pk_bf16_f32 v50, v56, v57
	v_cvt_pk_bf16_f32 v51, v58, v59
	v_mul_f32_e32 v57, v53, v53
	v_mul_f32_e32 v59, v55, v55
	v_cvt_pk_bf16_f32 v48, v60, v61
	v_mul_f32_e32 v61, v217, v217
	v_fmac_f32_e32 v218, v60, v60
	v_fmac_f32_e32 v219, v62, v62
	v_fmac_f32_e32 v57, v52, v52
	v_fmac_f32_e32 v59, v54, v54
	v_cvt_pk_bf16_f32 v49, v62, v63
	v_mul_f32_e32 v63, v215, v215
	v_fmac_f32_e32 v220, v56, v56
	v_fmac_f32_e32 v61, v216, v216
	v_add_f32_e32 v56, v218, v219
	v_add_f32_e32 v57, v57, v59
	v_fmac_f32_e32 v221, v58, v58
	v_fmac_f32_e32 v63, v214, v214
	v_add_f32_e32 v56, v220, v56
	v_add_f32_e32 v57, v61, v57
	v_add_f32_e32 v56, v221, v56
	v_add_f32_e32 v57, v63, v57
	v_add_f32_e32 v58, v56, v57
	ds_bpermute_b32 v59, v193, v58
	v_lshl_add_u64 v[56:57], s[82:83], 0, v[102:103]
	v_lshl_add_u64 v[56:57], v[172:173], 1, v[56:57]
	global_store_dwordx4 v[56:57], v[48:51], off
	s_waitcnt lgkmcnt(0)
	s_nop 0
	v_add_f32_e32 v48, v58, v59
	ds_bpermute_b32 v49, v175, v48
	v_cvt_pk_bf16_f32 v50, v52, v53
	v_cvt_pk_bf16_f32 v51, v54, v55
	v_cvt_pk_bf16_f32 v52, v216, v217
	v_cvt_pk_bf16_f32 v53, v214, v215
	global_store_dwordx4 v[56:57], v[50:53], off offset:256
	s_and_saveexec_b64 s[38:39], s[4:5]
	s_cbranch_execz .LBB0_1039
	s_waitcnt lgkmcnt(0)
	v_add_f32_e32 v48, v48, v49
	ds_write_b32 v187, v48 offset:2048
.LBB0_1039:
	s_or_b64 exec, exec, s[38:39]
	s_waitcnt vmcnt(15)
	v_lshlrev_b32_e32 v48, 16, v222
	s_waitcnt lgkmcnt(0)
	v_and_b32_e32 v49, 0xffff0000, v222
	v_lshlrev_b32_e32 v50, 16, v223
	v_and_b32_e32 v51, 0xffff0000, v223
	v_lshlrev_b32_e32 v52, 16, v224
	v_and_b32_e32 v53, 0xffff0000, v224
	v_lshlrev_b32_e32 v54, 16, v225
	v_and_b32_e32 v55, 0xffff0000, v225
	v_pk_add_f32 v[46:47], v[46:47], v[50:51]
	v_pk_add_f32 v[44:45], v[44:45], v[48:49]
	v_pk_add_f32 v[48:49], v[42:43], v[54:55]
	v_pk_add_f32 v[42:43], v[40:41], v[52:53]
	v_mul_f32_e32 v40, v45, v45
	v_mul_f32_e32 v41, v47, v47
	v_fmac_f32_e32 v40, v44, v44
	v_fmac_f32_e32 v41, v46, v46
	v_add_f32_e32 v40, v40, v41
	v_mul_f32_e32 v41, v43, v43
	v_fmac_f32_e32 v41, v42, v42
	v_add_f32_e32 v40, v41, v40
	v_mul_f32_e32 v41, v49, v49
	v_fmac_f32_e32 v41, v48, v48
	v_add_f32_e32 v52, v41, v40
	v_cvt_pk_bf16_f32 v40, v44, v45
	v_cvt_pk_bf16_f32 v41, v46, v47
	s_waitcnt vmcnt(14)
	v_lshlrev_b32_e32 v44, 16, v226
	v_and_b32_e32 v45, 0xffff0000, v226
	v_lshlrev_b32_e32 v46, 16, v227
	v_and_b32_e32 v47, 0xffff0000, v227
	v_cvt_pk_bf16_f32 v42, v42, v43
	v_cvt_pk_bf16_f32 v43, v48, v49
	v_lshlrev_b32_e32 v48, 16, v228
	v_and_b32_e32 v49, 0xffff0000, v228
	v_pk_add_f32 v[38:39], v[38:39], v[46:47]
	v_pk_add_f32 v[36:37], v[36:37], v[44:45]
	v_pk_add_f32 v[46:47], v[32:33], v[48:49]
	v_mul_f32_e32 v32, v37, v37
	v_mul_f32_e32 v33, v39, v39
	v_fmac_f32_e32 v32, v36, v36
	v_fmac_f32_e32 v33, v38, v38
	v_lshlrev_b32_e32 v50, 16, v229
	v_and_b32_e32 v51, 0xffff0000, v229
	v_add_f32_e32 v32, v32, v33
	v_mul_f32_e32 v33, v47, v47
	v_pk_add_f32 v[44:45], v[34:35], v[50:51]
	v_fmac_f32_e32 v33, v46, v46
	v_add_f32_e32 v32, v33, v32
	v_mul_f32_e32 v33, v45, v45
	v_fmac_f32_e32 v33, v44, v44
	v_add_f32_e32 v32, v33, v32
	v_add_f32_e32 v35, v52, v32
	ds_bpermute_b32 v50, v193, v35
	v_lshl_add_u64 v[32:33], s[82:83], 0, v[92:93]
	v_lshl_add_u64 v[48:49], v[172:173], 1, v[32:33]
	v_cvt_pk_bf16_f32 v34, v36, v37
	v_cvt_pk_bf16_f32 v36, v46, v47
	s_waitcnt lgkmcnt(0)
	v_add_f32_e32 v32, v35, v50
	ds_bpermute_b32 v33, v175, v32
	v_cvt_pk_bf16_f32 v35, v38, v39
	v_cvt_pk_bf16_f32 v37, v44, v45
	global_store_dwordx4 v[48:49], v[40:43], off
	global_store_dwordx4 v[48:49], v[34:37], off offset:256
	s_and_saveexec_b64 s[38:39], s[4:5]
	s_cbranch_execz .LBB0_1041
	s_waitcnt lgkmcnt(0)
	v_add_f32_e32 v32, v32, v33
	ds_write_b32 v187, v32 offset:2304
.LBB0_1041:
	s_or_b64 exec, exec, s[38:39]
	s_waitcnt vmcnt(15)
	v_lshlrev_b32_e32 v32, 16, v230
	s_waitcnt lgkmcnt(0)
	v_and_b32_e32 v33, 0xffff0000, v230
	v_lshlrev_b32_e32 v34, 16, v231
	v_and_b32_e32 v35, 0xffff0000, v231
	v_lshlrev_b32_e32 v36, 16, v232
	v_and_b32_e32 v37, 0xffff0000, v232
	v_lshlrev_b32_e32 v38, 16, v233
	v_and_b32_e32 v39, 0xffff0000, v233
	v_pk_add_f32 v[30:31], v[30:31], v[34:35]
	v_pk_add_f32 v[28:29], v[28:29], v[32:33]
	v_pk_add_f32 v[32:33], v[26:27], v[38:39]
	v_pk_add_f32 v[26:27], v[24:25], v[36:37]
	v_mul_f32_e32 v24, v29, v29
	v_mul_f32_e32 v25, v31, v31
	v_fmac_f32_e32 v24, v28, v28
	v_fmac_f32_e32 v25, v30, v30
	v_add_f32_e32 v24, v24, v25
	v_mul_f32_e32 v25, v27, v27
	v_fmac_f32_e32 v25, v26, v26
	v_add_f32_e32 v24, v25, v24
	v_mul_f32_e32 v25, v33, v33
	v_fmac_f32_e32 v25, v32, v32
	v_add_f32_e32 v36, v25, v24
	v_cvt_pk_bf16_f32 v24, v28, v29
	v_cvt_pk_bf16_f32 v25, v30, v31
	s_waitcnt vmcnt(14)
	v_lshlrev_b32_e32 v28, 16, v234
	v_and_b32_e32 v29, 0xffff0000, v234
	v_lshlrev_b32_e32 v30, 16, v235
	v_and_b32_e32 v31, 0xffff0000, v235
	v_cvt_pk_bf16_f32 v26, v26, v27
	v_cvt_pk_bf16_f32 v27, v32, v33
	v_lshlrev_b32_e32 v32, 16, v236
	v_and_b32_e32 v33, 0xffff0000, v236
	v_pk_add_f32 v[22:23], v[22:23], v[30:31]
	v_pk_add_f32 v[20:21], v[20:21], v[28:29]
	v_pk_add_f32 v[30:31], v[16:17], v[32:33]
	v_mul_f32_e32 v16, v21, v21
	v_mul_f32_e32 v17, v23, v23
	v_fmac_f32_e32 v16, v20, v20
	v_fmac_f32_e32 v17, v22, v22
	v_lshlrev_b32_e32 v34, 16, v237
	v_and_b32_e32 v35, 0xffff0000, v237
	v_add_f32_e32 v16, v16, v17
	v_mul_f32_e32 v17, v31, v31
	v_pk_add_f32 v[28:29], v[18:19], v[34:35]
	v_fmac_f32_e32 v17, v30, v30
	v_add_f32_e32 v16, v17, v16
	v_mul_f32_e32 v17, v29, v29
	v_fmac_f32_e32 v17, v28, v28
	v_add_f32_e32 v16, v17, v16
	v_add_f32_e32 v19, v36, v16
	ds_bpermute_b32 v34, v193, v19
	v_lshl_add_u64 v[16:17], s[82:83], 0, v[90:91]
	v_lshl_add_u64 v[32:33], v[172:173], 1, v[16:17]
	v_cvt_pk_bf16_f32 v18, v20, v21
	v_cvt_pk_bf16_f32 v20, v30, v31
	s_waitcnt lgkmcnt(0)
	v_add_f32_e32 v16, v19, v34
	ds_bpermute_b32 v17, v175, v16
	v_cvt_pk_bf16_f32 v19, v22, v23
	v_cvt_pk_bf16_f32 v21, v28, v29
	global_store_dwordx4 v[32:33], v[24:27], off
	global_store_dwordx4 v[32:33], v[18:21], off offset:256
	s_and_saveexec_b64 s[38:39], s[4:5]
	s_cbranch_execz .LBB0_1043
	s_waitcnt lgkmcnt(0)
	v_add_f32_e32 v16, v16, v17
	ds_write_b32 v187, v16 offset:2560
.LBB0_1043:
	s_or_b64 exec, exec, s[38:39]
	s_waitcnt vmcnt(15)
	v_lshlrev_b32_e32 v16, 16, v238
	s_waitcnt lgkmcnt(0)
	v_and_b32_e32 v17, 0xffff0000, v238
	v_lshlrev_b32_e32 v18, 16, v239
	v_and_b32_e32 v19, 0xffff0000, v239
	v_lshlrev_b32_e32 v20, 16, v240
	v_and_b32_e32 v21, 0xffff0000, v240
	v_lshlrev_b32_e32 v22, 16, v241
	v_and_b32_e32 v23, 0xffff0000, v241
	v_pk_add_f32 v[14:15], v[14:15], v[18:19]
	v_pk_add_f32 v[12:13], v[12:13], v[16:17]
	v_pk_add_f32 v[16:17], v[10:11], v[22:23]
	v_pk_add_f32 v[10:11], v[8:9], v[20:21]
	v_mul_f32_e32 v8, v13, v13
	v_mul_f32_e32 v9, v15, v15
	v_fmac_f32_e32 v8, v12, v12
	v_fmac_f32_e32 v9, v14, v14
	v_add_f32_e32 v8, v8, v9
	v_mul_f32_e32 v9, v11, v11
	v_fmac_f32_e32 v9, v10, v10
	v_add_f32_e32 v8, v9, v8
	v_mul_f32_e32 v9, v17, v17
	v_fmac_f32_e32 v9, v16, v16
	v_add_f32_e32 v20, v9, v8
	v_cvt_pk_bf16_f32 v8, v12, v13
	v_cvt_pk_bf16_f32 v9, v14, v15
	s_waitcnt vmcnt(6)
	v_lshlrev_b32_e32 v12, 16, v64
	v_and_b32_e32 v13, 0xffff0000, v64
	v_lshlrev_b32_e32 v14, 16, v65
	v_and_b32_e32 v15, 0xffff0000, v65
	v_cvt_pk_bf16_f32 v10, v10, v11
	v_cvt_pk_bf16_f32 v11, v16, v17
	v_lshlrev_b32_e32 v16, 16, v66
	v_and_b32_e32 v17, 0xffff0000, v66
	v_pk_add_f32 v[6:7], v[6:7], v[14:15]
	v_pk_add_f32 v[4:5], v[4:5], v[12:13]
	v_pk_add_f32 v[14:15], v[0:1], v[16:17]
	v_mul_f32_e32 v0, v5, v5
	v_mul_f32_e32 v1, v7, v7
	v_fmac_f32_e32 v0, v4, v4
	v_fmac_f32_e32 v1, v6, v6
	v_lshlrev_b32_e32 v18, 16, v67
	v_and_b32_e32 v19, 0xffff0000, v67
	v_add_f32_e32 v0, v0, v1
	v_mul_f32_e32 v1, v15, v15
	v_pk_add_f32 v[12:13], v[2:3], v[18:19]
	v_fmac_f32_e32 v1, v14, v14
	v_add_f32_e32 v0, v1, v0
	v_mul_f32_e32 v1, v13, v13
	v_fmac_f32_e32 v1, v12, v12
	v_add_f32_e32 v0, v1, v0
	v_add_f32_e32 v3, v20, v0
	ds_bpermute_b32 v18, v193, v3
	v_lshl_add_u64 v[0:1], s[82:83], 0, v[88:89]
	v_lshl_add_u64 v[16:17], v[172:173], 1, v[0:1]
	v_cvt_pk_bf16_f32 v2, v4, v5
	v_cvt_pk_bf16_f32 v4, v14, v15
	s_waitcnt lgkmcnt(0)
	v_add_f32_e32 v0, v3, v18
	ds_bpermute_b32 v1, v175, v0
	v_cvt_pk_bf16_f32 v3, v6, v7
	v_cvt_pk_bf16_f32 v5, v12, v13
	global_store_dwordx4 v[16:17], v[8:11], off
	global_store_dwordx4 v[16:17], v[2:5], off offset:256
	s_and_saveexec_b64 s[38:39], s[4:5]
	s_cbranch_execz .LBB0_1045
	s_waitcnt lgkmcnt(0)
	v_add_f32_e32 v0, v0, v1
	ds_write_b32 v187, v0 offset:2816

.LBB0_1327:
	s_ashr_i32 s31, s30, 31
	s_lshl_b64 s[30:31], s[30:31], 8
	v_or_b32_e32 v172, s30, v160
	s_lshl_b32 s30, s62, 8
	v_mov_b32_e32 v173, s31
	v_add_u32_e32 v174, s30, v161
	v_lshlrev_b64 v[202:203], 1, v[172:173]
	v_ashrrev_i32_e32 v175, 31, v174
	v_lshl_add_u64 v[176:177], s[82:83], 0, v[202:203]
	v_lshlrev_b64 v[204:205], 11, v[174:175]
	v_lshl_add_u64 v[128:129], v[176:177], 0, v[204:205]
	global_load_dwordx4 v[194:197], v[128:129], off
	global_load_dwordx4 v[198:201], v[128:129], off offset:256
	v_or_b32_e32 v128, 16, v174
	v_or_b32_e32 v130, 32, v174
	v_or_b32_e32 v132, 48, v174
	v_ashrrev_i32_e32 v129, 31, v128
	v_ashrrev_i32_e32 v131, 31, v130
	v_ashrrev_i32_e32 v133, 31, v132
	v_lshlrev_b64 v[182:183], 11, v[128:129]
	v_lshlrev_b64 v[180:181], 11, v[130:131]
	v_lshlrev_b64 v[178:179], 11, v[132:133]
	v_lshl_add_u64 v[128:129], v[176:177], 0, v[182:183]
	v_lshl_add_u64 v[130:131], v[176:177], 0, v[180:181]
	v_lshl_add_u64 v[206:207], v[176:177], 0, v[178:179]
	global_load_dwordx4 v[148:151], v[128:129], off
	global_load_dwordx4 v[144:147], v[128:129], off offset:256
	global_load_dwordx4 v[140:143], v[130:131], off
	global_load_dwordx4 v[136:139], v[130:131], off offset:256
	global_load_dwordx4 v[132:135], v[206:207], off
	s_nop 0
	global_load_dwordx4 v[128:131], v[206:207], off offset:256
	v_and_b32_e32 v193, 64, v192
	v_xor_b32_e32 v175, 16, v192
	v_add_u32_e32 v193, 64, v193
	v_xor_b32_e32 v206, 32, v192
	v_cmp_lt_i32_e32 vcc, v175, v193
	v_add_u32_e32 v218, 0x80, v174
	v_ashrrev_i32_e32 v219, 31, v218
	v_lshlrev_b64 v[218:219], 11, v[218:219]
	v_lshl_add_u64 v[218:219], v[176:177], 0, v[218:219]
	global_load_dwordx4 v[214:217], v[218:219], off
	global_load_dwordx4 v[218:221], v[218:219], off offset:256
	v_add_u32_e32 v226, 0x90, v174
	v_ashrrev_i32_e32 v227, 31, v226
	v_lshlrev_b64 v[226:227], 11, v[226:227]
	v_lshl_add_u64 v[226:227], v[176:177], 0, v[226:227]
	global_load_dwordx4 v[222:225], v[226:227], off
	global_load_dwordx4 v[226:229], v[226:227], off offset:256
	v_add_u32_e32 v234, 0xa0, v174
	v_ashrrev_i32_e32 v235, 31, v234
	v_lshlrev_b64 v[234:235], 11, v[234:235]
	v_lshl_add_u64 v[234:235], v[176:177], 0, v[234:235]
	global_load_dwordx4 v[230:233], v[234:235], off
	global_load_dwordx4 v[234:237], v[234:235], off offset:256
	v_add_u32_e32 v238, 0xb0, v174
	v_ashrrev_i32_e32 v239, 31, v238
	v_lshlrev_b64 v[238:239], 11, v[238:239]
	v_lshl_add_u64 v[238:239], v[176:177], 0, v[238:239]
	global_load_dwordx4 v[238:241], v[238:239], off
	s_waitcnt vmcnt(7)
	v_and_b32_e32 v207, 0xffff0000, v194
	v_cndmask_b32_e32 v175, v192, v175, vcc
	v_cmp_lt_i32_e32 vcc, v206, v193
	v_lshlrev_b32_e32 v193, 2, v175
	v_lshlrev_b32_e32 v208, 16, v196
	v_cndmask_b32_e32 v206, v192, v206, vcc
	v_lshlrev_b32_e32 v175, 2, v206
	v_lshlrev_b32_e32 v206, 16, v194
	v_lshlrev_b32_e32 v194, 16, v195
	v_and_b32_e32 v195, 0xffff0000, v195
	v_and_b32_e32 v209, 0xffff0000, v196
	v_lshlrev_b32_e32 v196, 16, v197
	v_and_b32_e32 v197, 0xffff0000, v197
	v_lshlrev_b32_e32 v210, 16, v198
	v_and_b32_e32 v211, 0xffff0000, v198
	v_lshlrev_b32_e32 v198, 16, v199
	v_and_b32_e32 v199, 0xffff0000, v199
	v_lshlrev_b32_e32 v212, 16, v200
	v_and_b32_e32 v213, 0xffff0000, v200
	v_lshlrev_b32_e32 v200, 16, v201
	v_and_b32_e32 v201, 0xffff0000, v201
	v_pk_fma_f32 v[126:127], v[126:127], 0.5, v[194:195] op_sel_hi:[1,0,1]
	v_pk_fma_f32 v[124:125], v[124:125], 0.5, v[206:207] op_sel_hi:[1,0,1]
	v_pk_fma_f32 v[122:123], v[122:123], 0.5, v[196:197] op_sel_hi:[1,0,1]
	v_pk_fma_f32 v[120:121], v[120:121], 0.5, v[208:209] op_sel_hi:[1,0,1]
	v_pk_fma_f32 v[118:119], v[118:119], 0.5, v[198:199] op_sel_hi:[1,0,1]
	v_pk_fma_f32 v[116:117], v[116:117], 0.5, v[210:211] op_sel_hi:[1,0,1]
	v_pk_fma_f32 v[194:195], v[114:115], 0.5, v[200:201] op_sel_hi:[1,0,1]
	v_pk_fma_f32 v[196:197], v[112:113], 0.5, v[212:213] op_sel_hi:[1,0,1]
	v_mul_f32_e32 v198, v125, v125
	v_mul_f32_e32 v199, v127, v127
	v_mul_f32_e32 v200, v121, v121
	v_mul_f32_e32 v201, v123, v123
	v_cvt_pk_bf16_f32 v114, v120, v121
	v_cvt_pk_bf16_f32 v115, v122, v123
	v_mul_f32_e32 v121, v117, v117
	v_mul_f32_e32 v123, v119, v119
	v_cvt_pk_bf16_f32 v112, v124, v125
	v_mul_f32_e32 v125, v197, v197
	v_fmac_f32_e32 v198, v124, v124
	v_fmac_f32_e32 v199, v126, v126
	v_fmac_f32_e32 v121, v116, v116
	v_fmac_f32_e32 v123, v118, v118
	v_cvt_pk_bf16_f32 v113, v126, v127
	v_mul_f32_e32 v127, v195, v195
	v_fmac_f32_e32 v200, v120, v120
	v_fmac_f32_e32 v125, v196, v196
	v_add_f32_e32 v120, v198, v199
	v_add_f32_e32 v121, v121, v123
	v_fmac_f32_e32 v201, v122, v122
	v_fmac_f32_e32 v127, v194, v194
	v_add_f32_e32 v120, v200, v120
	v_add_f32_e32 v121, v125, v121
	v_add_f32_e32 v120, v201, v120
	v_add_f32_e32 v121, v127, v121
	v_add_f32_e32 v122, v120, v121
	ds_bpermute_b32 v123, v193, v122
	v_lshl_add_u64 v[120:121], s[82:83], 0, v[204:205]
	v_lshl_add_u64 v[120:121], v[120:121], 0, v[202:203]
	global_store_dwordx4 v[120:121], v[112:115], off
	s_waitcnt lgkmcnt(0)
	s_nop 0
	v_add_f32_e32 v112, v122, v123
	ds_bpermute_b32 v113, v175, v112
	v_cvt_pk_bf16_f32 v114, v116, v117
	v_cvt_pk_bf16_f32 v115, v118, v119
	v_cvt_pk_bf16_f32 v116, v196, v197
	v_cvt_pk_bf16_f32 v117, v194, v195
	global_store_dwordx4 v[120:121], v[114:117], off offset:256
	s_and_saveexec_b64 s[34:35], s[4:5]
	s_cbranch_execz .LBB0_1329
	s_waitcnt lgkmcnt(0)
	v_add_f32_e32 v112, v112, v113
	ds_write_b32 v187, v112

.LBB0_1335:
	s_or_b64 exec, exec, s[34:35]
	v_add_u32_e32 v64, 0x80, v174
	s_waitcnt lgkmcnt(0)
	v_ashrrev_i32_e32 v65, 31, v64
	v_lshlrev_b64 v[102:103], 11, v[64:65]
	v_lshl_add_u64 v[64:65], v[176:177], 0, v[102:103]
	v_add_u32_e32 v64, 0x90, v174
	v_add_u32_e32 v66, 0xa0, v174
	v_add_u32_e32 v68, 0xb0, v174
	v_ashrrev_i32_e32 v65, 31, v64
	v_ashrrev_i32_e32 v67, 31, v66
	v_ashrrev_i32_e32 v69, 31, v68
	v_lshlrev_b64 v[92:93], 11, v[64:65]
	v_lshlrev_b64 v[90:91], 11, v[66:67]
	v_lshlrev_b64 v[88:89], 11, v[68:69]
	v_lshl_add_u64 v[64:65], v[176:177], 0, v[92:93]
	v_lshl_add_u64 v[66:67], v[176:177], 0, v[90:91]
	v_lshl_add_u64 v[104:105], v[176:177], 0, v[88:89]
	s_nop 0
	global_load_dwordx4 v[64:67], v[104:105], off offset:256
	s_waitcnt vmcnt(15)
	v_lshlrev_b32_e32 v104, 16, v214
	v_and_b32_e32 v105, 0xffff0000, v214
	v_lshlrev_b32_e32 v214, 16, v215
	v_and_b32_e32 v215, 0xffff0000, v215
	v_lshlrev_b32_e32 v106, 16, v216
	v_and_b32_e32 v107, 0xffff0000, v216
	v_lshlrev_b32_e32 v216, 16, v217
	v_and_b32_e32 v217, 0xffff0000, v217
	s_waitcnt vmcnt(14)
	v_lshlrev_b32_e32 v108, 16, v218
	v_and_b32_e32 v109, 0xffff0000, v218
	v_lshlrev_b32_e32 v218, 16, v219
	v_and_b32_e32 v219, 0xffff0000, v219
	v_lshlrev_b32_e32 v110, 16, v220
	v_and_b32_e32 v111, 0xffff0000, v220
	v_lshlrev_b32_e32 v220, 16, v221
	v_and_b32_e32 v221, 0xffff0000, v221
	v_pk_fma_f32 v[62:63], v[62:63], 0.5, v[214:215] op_sel_hi:[1,0,1]
	v_pk_fma_f32 v[60:61], v[60:61], 0.5, v[104:105] op_sel_hi:[1,0,1]
	v_pk_fma_f32 v[58:59], v[58:59], 0.5, v[216:217] op_sel_hi:[1,0,1]
	v_pk_fma_f32 v[56:57], v[56:57], 0.5, v[106:107] op_sel_hi:[1,0,1]
	v_pk_fma_f32 v[54:55], v[54:55], 0.5, v[218:219] op_sel_hi:[1,0,1]
	v_pk_fma_f32 v[52:53], v[52:53], 0.5, v[108:109] op_sel_hi:[1,0,1]
	v_pk_fma_f32 v[214:215], v[50:51], 0.5, v[220:221] op_sel_hi:[1,0,1]
	v_pk_fma_f32 v[216:217], v[48:49], 0.5, v[110:111] op_sel_hi:[1,0,1]
	v_mul_f32_e32 v218, v61, v61
	v_mul_f32_e32 v219, v63, v63
	v_mul_f32_e32 v220, v57, v57
	v_mul_f32_e32 v221, v59, v59
	v_cvt_pk_bf16_f32 v50, v56, v57
	v_cvt_pk_bf16_f32 v51, v58, v59
	v_mul_f32_e32 v57, v53, v53
	v_mul_f32_e32 v59, v55, v55
	v_cvt_pk_bf16_f32 v48, v60, v61
	v_mul_f32_e32 v61, v217, v217
	v_fmac_f32_e32 v218, v60, v60
	v_fmac_f32_e32 v219, v62, v62
	v_fmac_f32_e32 v57, v52, v52
	v_fmac_f32_e32 v59, v54, v54
	v_cvt_pk_bf16_f32 v49, v62, v63
	v_mul_f32_e32 v63, v215, v215
	v_fmac_f32_e32 v220, v56, v56
	v_fmac_f32_e32 v61, v216, v216
	v_add_f32_e32 v56, v218, v219
	v_add_f32_e32 v57, v57, v59
	v_fmac_f32_e32 v221, v58, v58
	v_fmac_f32_e32 v63, v214, v214
	v_add_f32_e32 v56, v220, v56
	v_add_f32_e32 v57, v61, v57
	v_add_f32_e32 v56, v221, v56
	v_add_f32_e32 v57, v63, v57
	v_add_f32_e32 v58, v56, v57
	ds_bpermute_b32 v59, v193, v58
	v_lshl_add_u64 v[56:57], s[82:83], 0, v[102:103]
	v_lshl_add_u64 v[56:57], v[172:173], 1, v[56:57]
	global_store_dwordx4 v[56:57], v[48:51], off
	s_waitcnt lgkmcnt(0)
	s_nop 0
	v_add_f32_e32 v48, v58, v59
	ds_bpermute_b32 v49, v175, v48
	v_cvt_pk_bf16_f32 v50, v52, v53
	v_cvt_pk_bf16_f32 v51, v54, v55
	v_cvt_pk_bf16_f32 v52, v216, v217
	v_cvt_pk_bf16_f32 v53, v214, v215
	global_store_dwordx4 v[56:57], v[50:53], off offset:256
	s_and_saveexec_b64 s[34:35], s[4:5]
	s_cbranch_execz .LBB0_1337
	s_waitcnt lgkmcnt(0)
	v_add_f32_e32 v48, v48, v49
	ds_write_b32 v187, v48 offset:2048
.LBB0_1337:
	s_or_b64 exec, exec, s[34:35]
	s_waitcnt vmcnt(15)
	v_lshlrev_b32_e32 v48, 16, v222
	s_waitcnt lgkmcnt(0)
	v_and_b32_e32 v49, 0xffff0000, v222
	v_lshlrev_b32_e32 v50, 16, v223
	v_and_b32_e32 v51, 0xffff0000, v223
	v_lshlrev_b32_e32 v52, 16, v224
	v_and_b32_e32 v53, 0xffff0000, v224
	v_lshlrev_b32_e32 v54, 16, v225
	v_and_b32_e32 v55, 0xffff0000, v225
	v_pk_fma_f32 v[46:47], v[46:47], 0.5, v[50:51] op_sel_hi:[1,0,1]
	v_pk_fma_f32 v[44:45], v[44:45], 0.5, v[48:49] op_sel_hi:[1,0,1]
	v_pk_fma_f32 v[48:49], v[42:43], 0.5, v[54:55] op_sel_hi:[1,0,1]
	v_pk_fma_f32 v[42:43], v[40:41], 0.5, v[52:53] op_sel_hi:[1,0,1]
	v_mul_f32_e32 v40, v45, v45
	v_mul_f32_e32 v41, v47, v47
	v_fmac_f32_e32 v40, v44, v44
	v_fmac_f32_e32 v41, v46, v46
	v_add_f32_e32 v40, v40, v41
	v_mul_f32_e32 v41, v43, v43
	v_fmac_f32_e32 v41, v42, v42
	v_add_f32_e32 v40, v41, v40
	v_mul_f32_e32 v41, v49, v49
	v_fmac_f32_e32 v41, v48, v48
	v_add_f32_e32 v52, v41, v40
	v_cvt_pk_bf16_f32 v40, v44, v45
	v_cvt_pk_bf16_f32 v41, v46, v47
	s_waitcnt vmcnt(14)
	v_lshlrev_b32_e32 v44, 16, v226
	v_and_b32_e32 v45, 0xffff0000, v226
	v_lshlrev_b32_e32 v46, 16, v227
	v_and_b32_e32 v47, 0xffff0000, v227
	v_cvt_pk_bf16_f32 v42, v42, v43
	v_cvt_pk_bf16_f32 v43, v48, v49
	v_lshlrev_b32_e32 v48, 16, v228
	v_and_b32_e32 v49, 0xffff0000, v228
	v_pk_fma_f32 v[38:39], v[38:39], 0.5, v[46:47] op_sel_hi:[1,0,1]
	v_pk_fma_f32 v[36:37], v[36:37], 0.5, v[44:45] op_sel_hi:[1,0,1]
	v_pk_fma_f32 v[46:47], v[32:33], 0.5, v[48:49] op_sel_hi:[1,0,1]
	v_mul_f32_e32 v32, v37, v37
	v_mul_f32_e32 v33, v39, v39
	v_fmac_f32_e32 v32, v36, v36
	v_fmac_f32_e32 v33, v38, v38
	v_lshlrev_b32_e32 v50, 16, v229
	v_and_b32_e32 v51, 0xffff0000, v229
	v_add_f32_e32 v32, v32, v33
	v_mul_f32_e32 v33, v47, v47
	v_pk_fma_f32 v[44:45], v[34:35], 0.5, v[50:51] op_sel_hi:[1,0,1]
	v_fmac_f32_e32 v33, v46, v46
	v_add_f32_e32 v32, v33, v32
	v_mul_f32_e32 v33, v45, v45
	v_fmac_f32_e32 v33, v44, v44
	v_add_f32_e32 v32, v33, v32
	v_add_f32_e32 v35, v52, v32
	ds_bpermute_b32 v50, v193, v35
	v_lshl_add_u64 v[32:33], s[82:83], 0, v[92:93]
	v_lshl_add_u64 v[48:49], v[172:173], 1, v[32:33]
	v_cvt_pk_bf16_f32 v34, v36, v37
	v_cvt_pk_bf16_f32 v36, v46, v47
	s_waitcnt lgkmcnt(0)
	v_add_f32_e32 v32, v35, v50
	ds_bpermute_b32 v33, v175, v32
	v_cvt_pk_bf16_f32 v35, v38, v39
	v_cvt_pk_bf16_f32 v37, v44, v45
	global_store_dwordx4 v[48:49], v[40:43], off
	global_store_dwordx4 v[48:49], v[34:37], off offset:256
	s_and_saveexec_b64 s[34:35], s[4:5]
	s_cbranch_execz .LBB0_1339
	s_waitcnt lgkmcnt(0)
	v_add_f32_e32 v32, v32, v33
	ds_write_b32 v187, v32 offset:2304
.LBB0_1339:
	s_or_b64 exec, exec, s[34:35]
	s_waitcnt vmcnt(15)
	v_lshlrev_b32_e32 v32, 16, v230
	s_waitcnt lgkmcnt(0)
	v_and_b32_e32 v33, 0xffff0000, v230
	v_lshlrev_b32_e32 v34, 16, v231
	v_and_b32_e32 v35, 0xffff0000, v231
	v_lshlrev_b32_e32 v36, 16, v232
	v_and_b32_e32 v37, 0xffff0000, v232
	v_lshlrev_b32_e32 v38, 16, v233
	v_and_b32_e32 v39, 0xffff0000, v233
	v_pk_fma_f32 v[30:31], v[30:31], 0.5, v[34:35] op_sel_hi:[1,0,1]
	v_pk_fma_f32 v[28:29], v[28:29], 0.5, v[32:33] op_sel_hi:[1,0,1]
	v_pk_fma_f32 v[32:33], v[26:27], 0.5, v[38:39] op_sel_hi:[1,0,1]
	v_pk_fma_f32 v[26:27], v[24:25], 0.5, v[36:37] op_sel_hi:[1,0,1]
	v_mul_f32_e32 v24, v29, v29
	v_mul_f32_e32 v25, v31, v31
	v_fmac_f32_e32 v24, v28, v28
	v_fmac_f32_e32 v25, v30, v30
	v_add_f32_e32 v24, v24, v25
	v_mul_f32_e32 v25, v27, v27
	v_fmac_f32_e32 v25, v26, v26
	v_add_f32_e32 v24, v25, v24
	v_mul_f32_e32 v25, v33, v33
	v_fmac_f32_e32 v25, v32, v32
	v_add_f32_e32 v36, v25, v24
	v_cvt_pk_bf16_f32 v24, v28, v29
	v_cvt_pk_bf16_f32 v25, v30, v31
	s_waitcnt vmcnt(14)
	v_lshlrev_b32_e32 v28, 16, v234
	v_and_b32_e32 v29, 0xffff0000, v234
	v_lshlrev_b32_e32 v30, 16, v235
	v_and_b32_e32 v31, 0xffff0000, v235
	v_cvt_pk_bf16_f32 v26, v26, v27
	v_cvt_pk_bf16_f32 v27, v32, v33
	v_lshlrev_b32_e32 v32, 16, v236
	v_and_b32_e32 v33, 0xffff0000, v236
	v_pk_fma_f32 v[22:23], v[22:23], 0.5, v[30:31] op_sel_hi:[1,0,1]
	v_pk_fma_f32 v[20:21], v[20:21], 0.5, v[28:29] op_sel_hi:[1,0,1]
	v_pk_fma_f32 v[30:31], v[16:17], 0.5, v[32:33] op_sel_hi:[1,0,1]
	v_mul_f32_e32 v16, v21, v21
	v_mul_f32_e32 v17, v23, v23
	v_fmac_f32_e32 v16, v20, v20
	v_fmac_f32_e32 v17, v22, v22
	v_lshlrev_b32_e32 v34, 16, v237
	v_and_b32_e32 v35, 0xffff0000, v237
	v_add_f32_e32 v16, v16, v17
	v_mul_f32_e32 v17, v31, v31
	v_pk_fma_f32 v[28:29], v[18:19], 0.5, v[34:35] op_sel_hi:[1,0,1]
	v_fmac_f32_e32 v17, v30, v30
	v_add_f32_e32 v16, v17, v16
	v_mul_f32_e32 v17, v29, v29
	v_fmac_f32_e32 v17, v28, v28
	v_add_f32_e32 v16, v17, v16
	v_add_f32_e32 v19, v36, v16
	ds_bpermute_b32 v34, v193, v19
	v_lshl_add_u64 v[16:17], s[82:83], 0, v[90:91]
	v_lshl_add_u64 v[32:33], v[172:173], 1, v[16:17]
	v_cvt_pk_bf16_f32 v18, v20, v21
	v_cvt_pk_bf16_f32 v20, v30, v31
	s_waitcnt lgkmcnt(0)
	v_add_f32_e32 v16, v19, v34
	ds_bpermute_b32 v17, v175, v16
	v_cvt_pk_bf16_f32 v19, v22, v23
	v_cvt_pk_bf16_f32 v21, v28, v29
	global_store_dwordx4 v[32:33], v[24:27], off
	global_store_dwordx4 v[32:33], v[18:21], off offset:256
	s_and_saveexec_b64 s[34:35], s[4:5]
	s_cbranch_execz .LBB0_1341
	s_waitcnt lgkmcnt(0)
	v_add_f32_e32 v16, v16, v17
	ds_write_b32 v187, v16 offset:2560
.LBB0_1341:
	s_or_b64 exec, exec, s[34:35]
	s_waitcnt vmcnt(15)
	v_lshlrev_b32_e32 v16, 16, v238
	s_waitcnt lgkmcnt(0)
	v_and_b32_e32 v17, 0xffff0000, v238
	v_lshlrev_b32_e32 v18, 16, v239
	v_and_b32_e32 v19, 0xffff0000, v239
	v_lshlrev_b32_e32 v20, 16, v240
	v_and_b32_e32 v21, 0xffff0000, v240
	v_lshlrev_b32_e32 v22, 16, v241
	v_and_b32_e32 v23, 0xffff0000, v241
	v_pk_fma_f32 v[14:15], v[14:15], 0.5, v[18:19] op_sel_hi:[1,0,1]
	v_pk_fma_f32 v[12:13], v[12:13], 0.5, v[16:17] op_sel_hi:[1,0,1]
	v_pk_fma_f32 v[16:17], v[10:11], 0.5, v[22:23] op_sel_hi:[1,0,1]
	v_pk_fma_f32 v[10:11], v[8:9], 0.5, v[20:21] op_sel_hi:[1,0,1]
	v_mul_f32_e32 v8, v13, v13
	v_mul_f32_e32 v9, v15, v15
	v_fmac_f32_e32 v8, v12, v12
	v_fmac_f32_e32 v9, v14, v14
	v_add_f32_e32 v8, v8, v9
	v_mul_f32_e32 v9, v11, v11
	v_fmac_f32_e32 v9, v10, v10
	v_add_f32_e32 v8, v9, v8
	v_mul_f32_e32 v9, v17, v17
	v_fmac_f32_e32 v9, v16, v16
	v_add_f32_e32 v20, v9, v8
	v_cvt_pk_bf16_f32 v8, v12, v13
	v_cvt_pk_bf16_f32 v9, v14, v15
	s_waitcnt vmcnt(6)
	v_lshlrev_b32_e32 v12, 16, v64
	v_and_b32_e32 v13, 0xffff0000, v64
	v_lshlrev_b32_e32 v14, 16, v65
	v_and_b32_e32 v15, 0xffff0000, v65
	v_cvt_pk_bf16_f32 v10, v10, v11
	v_cvt_pk_bf16_f32 v11, v16, v17
	v_lshlrev_b32_e32 v16, 16, v66
	v_and_b32_e32 v17, 0xffff0000, v66
	v_pk_fma_f32 v[6:7], v[6:7], 0.5, v[14:15] op_sel_hi:[1,0,1]
	v_pk_fma_f32 v[4:5], v[4:5], 0.5, v[12:13] op_sel_hi:[1,0,1]
	v_pk_fma_f32 v[14:15], v[0:1], 0.5, v[16:17] op_sel_hi:[1,0,1]
	v_mul_f32_e32 v0, v5, v5
	v_mul_f32_e32 v1, v7, v7
	v_fmac_f32_e32 v0, v4, v4
	v_fmac_f32_e32 v1, v6, v6
	v_lshlrev_b32_e32 v18, 16, v67
	v_and_b32_e32 v19, 0xffff0000, v67
	v_add_f32_e32 v0, v0, v1
	v_mul_f32_e32 v1, v15, v15
	v_pk_fma_f32 v[12:13], v[2:3], 0.5, v[18:19] op_sel_hi:[1,0,1]
	v_fmac_f32_e32 v1, v14, v14
	v_add_f32_e32 v0, v1, v0
	v_mul_f32_e32 v1, v13, v13
	v_fmac_f32_e32 v1, v12, v12
	v_add_f32_e32 v0, v1, v0
	v_add_f32_e32 v3, v20, v0
	ds_bpermute_b32 v18, v193, v3
	v_lshl_add_u64 v[0:1], s[82:83], 0, v[88:89]
	v_lshl_add_u64 v[16:17], v[172:173], 1, v[0:1]
	v_cvt_pk_bf16_f32 v2, v4, v5
	v_cvt_pk_bf16_f32 v4, v14, v15
	s_waitcnt lgkmcnt(0)
	v_add_f32_e32 v0, v3, v18
	ds_bpermute_b32 v1, v175, v0
	v_cvt_pk_bf16_f32 v3, v6, v7
	v_cvt_pk_bf16_f32 v5, v12, v13
	global_store_dwordx4 v[16:17], v[8:11], off
	global_store_dwordx4 v[16:17], v[2:5], off offset:256
	s_and_saveexec_b64 s[34:35], s[4:5]
	s_cbranch_execz .LBB0_1343
	s_waitcnt lgkmcnt(0)
	v_add_f32_e32 v0, v0, v1
	ds_write_b32 v187, v0 offset:2816

.LBB0_1633:
	s_ashr_i32 s21, s20, 31
	s_lshl_b64 s[20:21], s[20:21], 8
	v_or_b32_e32 v172, s20, v160
	s_lshl_b32 s20, s46, 8
	v_mov_b32_e32 v173, s21
	v_add_u32_e32 v174, s20, v161
	v_lshlrev_b64 v[202:203], 1, v[172:173]
	v_ashrrev_i32_e32 v175, 31, v174
	v_lshl_add_u64 v[176:177], s[82:83], 0, v[202:203]
	v_lshlrev_b64 v[204:205], 11, v[174:175]
	v_lshl_add_u64 v[128:129], v[176:177], 0, v[204:205]
	global_load_dwordx4 v[194:197], v[128:129], off
	global_load_dwordx4 v[198:201], v[128:129], off offset:256
	v_or_b32_e32 v128, 16, v174
	v_or_b32_e32 v130, 32, v174
	v_or_b32_e32 v132, 48, v174
	v_ashrrev_i32_e32 v129, 31, v128
	v_ashrrev_i32_e32 v131, 31, v130
	v_ashrrev_i32_e32 v133, 31, v132
	v_lshlrev_b64 v[182:183], 11, v[128:129]
	v_lshlrev_b64 v[180:181], 11, v[130:131]
	v_lshlrev_b64 v[178:179], 11, v[132:133]
	v_lshl_add_u64 v[128:129], v[176:177], 0, v[182:183]
	v_lshl_add_u64 v[130:131], v[176:177], 0, v[180:181]
	v_lshl_add_u64 v[206:207], v[176:177], 0, v[178:179]
	global_load_dwordx4 v[148:151], v[128:129], off
	global_load_dwordx4 v[144:147], v[128:129], off offset:256
	global_load_dwordx4 v[140:143], v[130:131], off
	global_load_dwordx4 v[136:139], v[130:131], off offset:256
	global_load_dwordx4 v[132:135], v[206:207], off
	s_nop 0
	global_load_dwordx4 v[128:131], v[206:207], off offset:256
	v_and_b32_e32 v193, 64, v192
	v_xor_b32_e32 v175, 16, v192
	v_add_u32_e32 v193, 64, v193
	v_xor_b32_e32 v206, 32, v192
	v_cmp_lt_i32_e32 vcc, v175, v193
	v_add_u32_e32 v218, 0x80, v174
	v_ashrrev_i32_e32 v219, 31, v218
	v_lshlrev_b64 v[218:219], 11, v[218:219]
	v_lshl_add_u64 v[218:219], v[176:177], 0, v[218:219]
	global_load_dwordx4 v[214:217], v[218:219], off
	global_load_dwordx4 v[218:221], v[218:219], off offset:256
	v_add_u32_e32 v226, 0x90, v174
	v_ashrrev_i32_e32 v227, 31, v226
	v_lshlrev_b64 v[226:227], 11, v[226:227]
	v_lshl_add_u64 v[226:227], v[176:177], 0, v[226:227]
	global_load_dwordx4 v[222:225], v[226:227], off
	global_load_dwordx4 v[226:229], v[226:227], off offset:256
	v_add_u32_e32 v234, 0xa0, v174
	v_ashrrev_i32_e32 v235, 31, v234
	v_lshlrev_b64 v[234:235], 11, v[234:235]
	v_lshl_add_u64 v[234:235], v[176:177], 0, v[234:235]
	global_load_dwordx4 v[230:233], v[234:235], off
	global_load_dwordx4 v[234:237], v[234:235], off offset:256
	v_add_u32_e32 v238, 0xb0, v174
	v_ashrrev_i32_e32 v239, 31, v238
	v_lshlrev_b64 v[238:239], 11, v[238:239]
	v_lshl_add_u64 v[238:239], v[176:177], 0, v[238:239]
	global_load_dwordx4 v[238:241], v[238:239], off
	s_waitcnt vmcnt(7)
	v_and_b32_e32 v207, 0xffff0000, v194
	v_cndmask_b32_e32 v175, v192, v175, vcc
	v_cmp_lt_i32_e32 vcc, v206, v193
	v_lshlrev_b32_e32 v193, 2, v175
	v_lshlrev_b32_e32 v208, 16, v196
	v_cndmask_b32_e32 v206, v192, v206, vcc
	v_lshlrev_b32_e32 v175, 2, v206
	v_lshlrev_b32_e32 v206, 16, v194
	v_lshlrev_b32_e32 v194, 16, v195
	v_and_b32_e32 v195, 0xffff0000, v195
	v_and_b32_e32 v209, 0xffff0000, v196
	v_lshlrev_b32_e32 v196, 16, v197
	v_and_b32_e32 v197, 0xffff0000, v197
	v_lshlrev_b32_e32 v210, 16, v198
	v_and_b32_e32 v211, 0xffff0000, v198
	v_lshlrev_b32_e32 v198, 16, v199
	v_and_b32_e32 v199, 0xffff0000, v199
	v_lshlrev_b32_e32 v212, 16, v200
	v_and_b32_e32 v213, 0xffff0000, v200
	v_lshlrev_b32_e32 v200, 16, v201
	v_and_b32_e32 v201, 0xffff0000, v201
	v_pk_fma_f32 v[126:127], v[126:127], 0.5, v[194:195] op_sel_hi:[1,0,1]
	v_pk_fma_f32 v[124:125], v[124:125], 0.5, v[206:207] op_sel_hi:[1,0,1]
	v_pk_fma_f32 v[122:123], v[122:123], 0.5, v[196:197] op_sel_hi:[1,0,1]
	v_pk_fma_f32 v[120:121], v[120:121], 0.5, v[208:209] op_sel_hi:[1,0,1]
	v_pk_fma_f32 v[118:119], v[118:119], 0.5, v[198:199] op_sel_hi:[1,0,1]
	v_pk_fma_f32 v[116:117], v[116:117], 0.5, v[210:211] op_sel_hi:[1,0,1]
	v_pk_fma_f32 v[194:195], v[114:115], 0.5, v[200:201] op_sel_hi:[1,0,1]
	v_pk_fma_f32 v[196:197], v[112:113], 0.5, v[212:213] op_sel_hi:[1,0,1]
	v_mul_f32_e32 v198, v125, v125
	v_mul_f32_e32 v199, v127, v127
	v_mul_f32_e32 v200, v121, v121
	v_mul_f32_e32 v201, v123, v123
	v_cvt_pk_bf16_f32 v114, v120, v121
	v_cvt_pk_bf16_f32 v115, v122, v123
	v_mul_f32_e32 v121, v117, v117
	v_mul_f32_e32 v123, v119, v119
	v_cvt_pk_bf16_f32 v112, v124, v125
	v_mul_f32_e32 v125, v197, v197
	v_fmac_f32_e32 v198, v124, v124
	v_fmac_f32_e32 v199, v126, v126
	v_fmac_f32_e32 v121, v116, v116
	v_fmac_f32_e32 v123, v118, v118
	v_cvt_pk_bf16_f32 v113, v126, v127
	v_mul_f32_e32 v127, v195, v195
	v_fmac_f32_e32 v200, v120, v120
	v_fmac_f32_e32 v125, v196, v196
	v_add_f32_e32 v120, v198, v199
	v_add_f32_e32 v121, v121, v123
	v_fmac_f32_e32 v201, v122, v122
	v_fmac_f32_e32 v127, v194, v194
	v_add_f32_e32 v120, v200, v120
	v_add_f32_e32 v121, v125, v121
	v_add_f32_e32 v120, v201, v120
	v_add_f32_e32 v121, v127, v121
	v_add_f32_e32 v122, v120, v121
	ds_bpermute_b32 v123, v193, v122
	v_lshl_add_u64 v[120:121], s[82:83], 0, v[204:205]
	v_lshl_add_u64 v[120:121], v[120:121], 0, v[202:203]
	global_store_dwordx4 v[120:121], v[112:115], off
	s_waitcnt lgkmcnt(0)
	s_nop 0
	v_add_f32_e32 v112, v122, v123
	ds_bpermute_b32 v113, v175, v112
	v_cvt_pk_bf16_f32 v114, v116, v117
	v_cvt_pk_bf16_f32 v115, v118, v119
	v_cvt_pk_bf16_f32 v116, v196, v197
	v_cvt_pk_bf16_f32 v117, v194, v195
	global_store_dwordx4 v[120:121], v[114:117], off offset:256
	s_and_saveexec_b64 s[22:23], s[4:5]
	s_cbranch_execz .LBB0_1635
	s_waitcnt lgkmcnt(0)
	v_add_f32_e32 v112, v112, v113
	ds_write_b32 v187, v112

.LBB0_1641:
	s_or_b64 exec, exec, s[22:23]
	v_add_u32_e32 v64, 0x80, v174
	s_waitcnt lgkmcnt(0)
	v_ashrrev_i32_e32 v65, 31, v64
	v_lshlrev_b64 v[102:103], 11, v[64:65]
	v_lshl_add_u64 v[64:65], v[176:177], 0, v[102:103]
	v_add_u32_e32 v64, 0x90, v174
	v_add_u32_e32 v66, 0xa0, v174
	v_add_u32_e32 v68, 0xb0, v174
	v_ashrrev_i32_e32 v65, 31, v64
	v_ashrrev_i32_e32 v67, 31, v66
	v_ashrrev_i32_e32 v69, 31, v68
	v_lshlrev_b64 v[92:93], 11, v[64:65]
	v_lshlrev_b64 v[90:91], 11, v[66:67]
	v_lshlrev_b64 v[88:89], 11, v[68:69]
	v_lshl_add_u64 v[64:65], v[176:177], 0, v[92:93]
	v_lshl_add_u64 v[66:67], v[176:177], 0, v[90:91]
	v_lshl_add_u64 v[104:105], v[176:177], 0, v[88:89]
	s_nop 0
	global_load_dwordx4 v[64:67], v[104:105], off offset:256
	s_waitcnt vmcnt(15)
	v_lshlrev_b32_e32 v104, 16, v214
	v_and_b32_e32 v105, 0xffff0000, v214
	v_lshlrev_b32_e32 v214, 16, v215
	v_and_b32_e32 v215, 0xffff0000, v215
	v_lshlrev_b32_e32 v106, 16, v216
	v_and_b32_e32 v107, 0xffff0000, v216
	v_lshlrev_b32_e32 v216, 16, v217
	v_and_b32_e32 v217, 0xffff0000, v217
	s_waitcnt vmcnt(14)
	v_lshlrev_b32_e32 v108, 16, v218
	v_and_b32_e32 v109, 0xffff0000, v218
	v_lshlrev_b32_e32 v218, 16, v219
	v_and_b32_e32 v219, 0xffff0000, v219
	v_lshlrev_b32_e32 v110, 16, v220
	v_and_b32_e32 v111, 0xffff0000, v220
	v_lshlrev_b32_e32 v220, 16, v221
	v_and_b32_e32 v221, 0xffff0000, v221
	v_pk_fma_f32 v[62:63], v[62:63], 0.5, v[214:215] op_sel_hi:[1,0,1]
	v_pk_fma_f32 v[60:61], v[60:61], 0.5, v[104:105] op_sel_hi:[1,0,1]
	v_pk_fma_f32 v[58:59], v[58:59], 0.5, v[216:217] op_sel_hi:[1,0,1]
	v_pk_fma_f32 v[56:57], v[56:57], 0.5, v[106:107] op_sel_hi:[1,0,1]
	v_pk_fma_f32 v[54:55], v[54:55], 0.5, v[218:219] op_sel_hi:[1,0,1]
	v_pk_fma_f32 v[52:53], v[52:53], 0.5, v[108:109] op_sel_hi:[1,0,1]
	v_pk_fma_f32 v[214:215], v[50:51], 0.5, v[220:221] op_sel_hi:[1,0,1]
	v_pk_fma_f32 v[216:217], v[48:49], 0.5, v[110:111] op_sel_hi:[1,0,1]
	v_mul_f32_e32 v218, v61, v61
	v_mul_f32_e32 v219, v63, v63
	v_mul_f32_e32 v220, v57, v57
	v_mul_f32_e32 v221, v59, v59
	v_cvt_pk_bf16_f32 v50, v56, v57
	v_cvt_pk_bf16_f32 v51, v58, v59
	v_mul_f32_e32 v57, v53, v53
	v_mul_f32_e32 v59, v55, v55
	v_cvt_pk_bf16_f32 v48, v60, v61
	v_mul_f32_e32 v61, v217, v217
	v_fmac_f32_e32 v218, v60, v60
	v_fmac_f32_e32 v219, v62, v62
	v_fmac_f32_e32 v57, v52, v52
	v_fmac_f32_e32 v59, v54, v54
	v_cvt_pk_bf16_f32 v49, v62, v63
	v_mul_f32_e32 v63, v215, v215
	v_fmac_f32_e32 v220, v56, v56
	v_fmac_f32_e32 v61, v216, v216
	v_add_f32_e32 v56, v218, v219
	v_add_f32_e32 v57, v57, v59
	v_fmac_f32_e32 v221, v58, v58
	v_fmac_f32_e32 v63, v214, v214
	v_add_f32_e32 v56, v220, v56
	v_add_f32_e32 v57, v61, v57
	v_add_f32_e32 v56, v221, v56
	v_add_f32_e32 v57, v63, v57
	v_add_f32_e32 v58, v56, v57
	ds_bpermute_b32 v59, v193, v58
	v_lshl_add_u64 v[56:57], s[82:83], 0, v[102:103]
	v_lshl_add_u64 v[56:57], v[172:173], 1, v[56:57]
	global_store_dwordx4 v[56:57], v[48:51], off
	s_waitcnt lgkmcnt(0)
	s_nop 0
	v_add_f32_e32 v48, v58, v59
	ds_bpermute_b32 v49, v175, v48
	v_cvt_pk_bf16_f32 v50, v52, v53
	v_cvt_pk_bf16_f32 v51, v54, v55
	v_cvt_pk_bf16_f32 v52, v216, v217
	v_cvt_pk_bf16_f32 v53, v214, v215
	global_store_dwordx4 v[56:57], v[50:53], off offset:256
	s_and_saveexec_b64 s[22:23], s[4:5]
	s_cbranch_execz .LBB0_1643
	s_waitcnt lgkmcnt(0)
	v_add_f32_e32 v48, v48, v49
	ds_write_b32 v187, v48 offset:2048
.LBB0_1643:
	s_or_b64 exec, exec, s[22:23]
	s_waitcnt vmcnt(15)
	v_lshlrev_b32_e32 v48, 16, v222
	s_waitcnt lgkmcnt(0)
	v_and_b32_e32 v49, 0xffff0000, v222
	v_lshlrev_b32_e32 v50, 16, v223
	v_and_b32_e32 v51, 0xffff0000, v223
	v_lshlrev_b32_e32 v52, 16, v224
	v_and_b32_e32 v53, 0xffff0000, v224
	v_lshlrev_b32_e32 v54, 16, v225
	v_and_b32_e32 v55, 0xffff0000, v225
	v_pk_fma_f32 v[46:47], v[46:47], 0.5, v[50:51] op_sel_hi:[1,0,1]
	v_pk_fma_f32 v[44:45], v[44:45], 0.5, v[48:49] op_sel_hi:[1,0,1]
	v_pk_fma_f32 v[48:49], v[42:43], 0.5, v[54:55] op_sel_hi:[1,0,1]
	v_pk_fma_f32 v[42:43], v[40:41], 0.5, v[52:53] op_sel_hi:[1,0,1]
	v_mul_f32_e32 v40, v45, v45
	v_mul_f32_e32 v41, v47, v47
	v_fmac_f32_e32 v40, v44, v44
	v_fmac_f32_e32 v41, v46, v46
	v_add_f32_e32 v40, v40, v41
	v_mul_f32_e32 v41, v43, v43
	v_fmac_f32_e32 v41, v42, v42
	v_add_f32_e32 v40, v41, v40
	v_mul_f32_e32 v41, v49, v49
	v_fmac_f32_e32 v41, v48, v48
	v_add_f32_e32 v52, v41, v40
	v_cvt_pk_bf16_f32 v40, v44, v45
	v_cvt_pk_bf16_f32 v41, v46, v47
	s_waitcnt vmcnt(14)
	v_lshlrev_b32_e32 v44, 16, v226
	v_and_b32_e32 v45, 0xffff0000, v226
	v_lshlrev_b32_e32 v46, 16, v227
	v_and_b32_e32 v47, 0xffff0000, v227
	v_cvt_pk_bf16_f32 v42, v42, v43
	v_cvt_pk_bf16_f32 v43, v48, v49
	v_lshlrev_b32_e32 v48, 16, v228
	v_and_b32_e32 v49, 0xffff0000, v228
	v_pk_fma_f32 v[38:39], v[38:39], 0.5, v[46:47] op_sel_hi:[1,0,1]
	v_pk_fma_f32 v[36:37], v[36:37], 0.5, v[44:45] op_sel_hi:[1,0,1]
	v_pk_fma_f32 v[46:47], v[32:33], 0.5, v[48:49] op_sel_hi:[1,0,1]
	v_mul_f32_e32 v32, v37, v37
	v_mul_f32_e32 v33, v39, v39
	v_fmac_f32_e32 v32, v36, v36
	v_fmac_f32_e32 v33, v38, v38
	v_lshlrev_b32_e32 v50, 16, v229
	v_and_b32_e32 v51, 0xffff0000, v229
	v_add_f32_e32 v32, v32, v33
	v_mul_f32_e32 v33, v47, v47
	v_pk_fma_f32 v[44:45], v[34:35], 0.5, v[50:51] op_sel_hi:[1,0,1]
	v_fmac_f32_e32 v33, v46, v46
	v_add_f32_e32 v32, v33, v32
	v_mul_f32_e32 v33, v45, v45
	v_fmac_f32_e32 v33, v44, v44
	v_add_f32_e32 v32, v33, v32
	v_add_f32_e32 v35, v52, v32
	ds_bpermute_b32 v50, v193, v35
	v_lshl_add_u64 v[32:33], s[82:83], 0, v[92:93]
	v_lshl_add_u64 v[48:49], v[172:173], 1, v[32:33]
	v_cvt_pk_bf16_f32 v34, v36, v37
	v_cvt_pk_bf16_f32 v36, v46, v47
	s_waitcnt lgkmcnt(0)
	v_add_f32_e32 v32, v35, v50
	ds_bpermute_b32 v33, v175, v32
	v_cvt_pk_bf16_f32 v35, v38, v39
	v_cvt_pk_bf16_f32 v37, v44, v45
	global_store_dwordx4 v[48:49], v[40:43], off
	global_store_dwordx4 v[48:49], v[34:37], off offset:256
	s_and_saveexec_b64 s[22:23], s[4:5]
	s_cbranch_execz .LBB0_1645
	s_waitcnt lgkmcnt(0)
	v_add_f32_e32 v32, v32, v33
	ds_write_b32 v187, v32 offset:2304
.LBB0_1645:
	s_or_b64 exec, exec, s[22:23]
	s_waitcnt vmcnt(15)
	v_lshlrev_b32_e32 v32, 16, v230
	s_waitcnt lgkmcnt(0)
	v_and_b32_e32 v33, 0xffff0000, v230
	v_lshlrev_b32_e32 v34, 16, v231
	v_and_b32_e32 v35, 0xffff0000, v231
	v_lshlrev_b32_e32 v36, 16, v232
	v_and_b32_e32 v37, 0xffff0000, v232
	v_lshlrev_b32_e32 v38, 16, v233
	v_and_b32_e32 v39, 0xffff0000, v233
	v_pk_fma_f32 v[30:31], v[30:31], 0.5, v[34:35] op_sel_hi:[1,0,1]
	v_pk_fma_f32 v[28:29], v[28:29], 0.5, v[32:33] op_sel_hi:[1,0,1]
	v_pk_fma_f32 v[32:33], v[26:27], 0.5, v[38:39] op_sel_hi:[1,0,1]
	v_pk_fma_f32 v[26:27], v[24:25], 0.5, v[36:37] op_sel_hi:[1,0,1]
	v_mul_f32_e32 v24, v29, v29
	v_mul_f32_e32 v25, v31, v31
	v_fmac_f32_e32 v24, v28, v28
	v_fmac_f32_e32 v25, v30, v30
	v_add_f32_e32 v24, v24, v25
	v_mul_f32_e32 v25, v27, v27
	v_fmac_f32_e32 v25, v26, v26
	v_add_f32_e32 v24, v25, v24
	v_mul_f32_e32 v25, v33, v33
	v_fmac_f32_e32 v25, v32, v32
	v_add_f32_e32 v36, v25, v24
	v_cvt_pk_bf16_f32 v24, v28, v29
	v_cvt_pk_bf16_f32 v25, v30, v31
	s_waitcnt vmcnt(14)
	v_lshlrev_b32_e32 v28, 16, v234
	v_and_b32_e32 v29, 0xffff0000, v234
	v_lshlrev_b32_e32 v30, 16, v235
	v_and_b32_e32 v31, 0xffff0000, v235
	v_cvt_pk_bf16_f32 v26, v26, v27
	v_cvt_pk_bf16_f32 v27, v32, v33
	v_lshlrev_b32_e32 v32, 16, v236
	v_and_b32_e32 v33, 0xffff0000, v236
	v_pk_fma_f32 v[22:23], v[22:23], 0.5, v[30:31] op_sel_hi:[1,0,1]
	v_pk_fma_f32 v[20:21], v[20:21], 0.5, v[28:29] op_sel_hi:[1,0,1]
	v_pk_fma_f32 v[30:31], v[16:17], 0.5, v[32:33] op_sel_hi:[1,0,1]
	v_mul_f32_e32 v16, v21, v21
	v_mul_f32_e32 v17, v23, v23
	v_fmac_f32_e32 v16, v20, v20
	v_fmac_f32_e32 v17, v22, v22
	v_lshlrev_b32_e32 v34, 16, v237
	v_and_b32_e32 v35, 0xffff0000, v237
	v_add_f32_e32 v16, v16, v17
	v_mul_f32_e32 v17, v31, v31
	v_pk_fma_f32 v[28:29], v[18:19], 0.5, v[34:35] op_sel_hi:[1,0,1]
	v_fmac_f32_e32 v17, v30, v30
	v_add_f32_e32 v16, v17, v16
	v_mul_f32_e32 v17, v29, v29
	v_fmac_f32_e32 v17, v28, v28
	v_add_f32_e32 v16, v17, v16
	v_add_f32_e32 v19, v36, v16
	ds_bpermute_b32 v34, v193, v19
	v_lshl_add_u64 v[16:17], s[82:83], 0, v[90:91]
	v_lshl_add_u64 v[32:33], v[172:173], 1, v[16:17]
	v_cvt_pk_bf16_f32 v18, v20, v21
	v_cvt_pk_bf16_f32 v20, v30, v31
	s_waitcnt lgkmcnt(0)
	v_add_f32_e32 v16, v19, v34
	ds_bpermute_b32 v17, v175, v16
	v_cvt_pk_bf16_f32 v19, v22, v23
	v_cvt_pk_bf16_f32 v21, v28, v29
	global_store_dwordx4 v[32:33], v[24:27], off
	global_store_dwordx4 v[32:33], v[18:21], off offset:256
	s_and_saveexec_b64 s[22:23], s[4:5]
	s_cbranch_execz .LBB0_1647
	s_waitcnt lgkmcnt(0)
	v_add_f32_e32 v16, v16, v17
	ds_write_b32 v187, v16 offset:2560
.LBB0_1647:
	s_or_b64 exec, exec, s[22:23]
	s_waitcnt vmcnt(15)
	v_lshlrev_b32_e32 v16, 16, v238
	s_waitcnt lgkmcnt(0)
	v_and_b32_e32 v17, 0xffff0000, v238
	v_lshlrev_b32_e32 v18, 16, v239
	v_and_b32_e32 v19, 0xffff0000, v239
	v_lshlrev_b32_e32 v20, 16, v240
	v_and_b32_e32 v21, 0xffff0000, v240
	v_lshlrev_b32_e32 v22, 16, v241
	v_and_b32_e32 v23, 0xffff0000, v241
	v_pk_fma_f32 v[14:15], v[14:15], 0.5, v[18:19] op_sel_hi:[1,0,1]
	v_pk_fma_f32 v[12:13], v[12:13], 0.5, v[16:17] op_sel_hi:[1,0,1]
	v_pk_fma_f32 v[16:17], v[10:11], 0.5, v[22:23] op_sel_hi:[1,0,1]
	v_pk_fma_f32 v[10:11], v[8:9], 0.5, v[20:21] op_sel_hi:[1,0,1]
	v_mul_f32_e32 v8, v13, v13
	v_mul_f32_e32 v9, v15, v15
	v_fmac_f32_e32 v8, v12, v12
	v_fmac_f32_e32 v9, v14, v14
	v_add_f32_e32 v8, v8, v9
	v_mul_f32_e32 v9, v11, v11
	v_fmac_f32_e32 v9, v10, v10
	v_add_f32_e32 v8, v9, v8
	v_mul_f32_e32 v9, v17, v17
	v_fmac_f32_e32 v9, v16, v16
	v_add_f32_e32 v20, v9, v8
	v_cvt_pk_bf16_f32 v8, v12, v13
	v_cvt_pk_bf16_f32 v9, v14, v15
	s_waitcnt vmcnt(6)
	v_lshlrev_b32_e32 v12, 16, v64
	v_and_b32_e32 v13, 0xffff0000, v64
	v_lshlrev_b32_e32 v14, 16, v65
	v_and_b32_e32 v15, 0xffff0000, v65
	v_cvt_pk_bf16_f32 v10, v10, v11
	v_cvt_pk_bf16_f32 v11, v16, v17
	v_lshlrev_b32_e32 v16, 16, v66
	v_and_b32_e32 v17, 0xffff0000, v66
	v_pk_fma_f32 v[6:7], v[6:7], 0.5, v[14:15] op_sel_hi:[1,0,1]
	v_pk_fma_f32 v[4:5], v[4:5], 0.5, v[12:13] op_sel_hi:[1,0,1]
	v_pk_fma_f32 v[14:15], v[0:1], 0.5, v[16:17] op_sel_hi:[1,0,1]
	v_mul_f32_e32 v0, v5, v5
	v_mul_f32_e32 v1, v7, v7
	v_fmac_f32_e32 v0, v4, v4
	v_fmac_f32_e32 v1, v6, v6
	v_lshlrev_b32_e32 v18, 16, v67
	v_and_b32_e32 v19, 0xffff0000, v67
	v_add_f32_e32 v0, v0, v1
	v_mul_f32_e32 v1, v15, v15
	v_pk_fma_f32 v[12:13], v[2:3], 0.5, v[18:19] op_sel_hi:[1,0,1]
	v_fmac_f32_e32 v1, v14, v14
	v_add_f32_e32 v0, v1, v0
	v_mul_f32_e32 v1, v13, v13
	v_fmac_f32_e32 v1, v12, v12
	v_add_f32_e32 v0, v1, v0
	v_add_f32_e32 v3, v20, v0
	ds_bpermute_b32 v18, v193, v3
	v_lshl_add_u64 v[0:1], s[82:83], 0, v[88:89]
	v_lshl_add_u64 v[16:17], v[172:173], 1, v[0:1]
	v_cvt_pk_bf16_f32 v2, v4, v5
	v_cvt_pk_bf16_f32 v4, v14, v15
	s_waitcnt lgkmcnt(0)
	v_add_f32_e32 v0, v3, v18
	ds_bpermute_b32 v1, v175, v0
	v_cvt_pk_bf16_f32 v3, v6, v7
	v_cvt_pk_bf16_f32 v5, v12, v13
	global_store_dwordx4 v[16:17], v[8:11], off
	global_store_dwordx4 v[16:17], v[2:5], off offset:256
	s_and_saveexec_b64 s[22:23], s[4:5]
	s_cbranch_execz .LBB0_1649
	s_waitcnt lgkmcnt(0)
	v_add_f32_e32 v0, v0, v1
	ds_write_b32 v187, v0 offset:2816

.LBB0_1889:
	s_ashr_i32 s27, s26, 31
	s_lshl_b64 s[26:27], s[26:27], 8
	s_lshl_b32 s24, s24, 8
	v_mov_b32_e32 v173, s27
	v_or_b32_e32 v172, s26, v160
	v_add_u32_e32 v174, s24, v161
	v_lshlrev_b64 v[202:203], 1, v[172:173]
	v_ashrrev_i32_e32 v175, 31, v174
	v_lshl_add_u64 v[176:177], s[82:83], 0, v[202:203]
	v_lshlrev_b64 v[204:205], 11, v[174:175]
	v_lshl_add_u64 v[128:129], v[176:177], 0, v[204:205]
	global_load_dwordx4 v[194:197], v[128:129], off
	global_load_dwordx4 v[198:201], v[128:129], off offset:256
	v_or_b32_e32 v128, 16, v174
	v_or_b32_e32 v130, 32, v174
	v_or_b32_e32 v132, 48, v174
	v_ashrrev_i32_e32 v129, 31, v128
	v_ashrrev_i32_e32 v131, 31, v130
	v_ashrrev_i32_e32 v133, 31, v132
	v_lshlrev_b64 v[182:183], 11, v[128:129]
	v_lshlrev_b64 v[180:181], 11, v[130:131]
	v_lshlrev_b64 v[178:179], 11, v[132:133]
	v_lshl_add_u64 v[128:129], v[176:177], 0, v[182:183]
	v_lshl_add_u64 v[130:131], v[176:177], 0, v[180:181]
	v_lshl_add_u64 v[192:193], v[176:177], 0, v[178:179]
	global_load_dwordx4 v[148:151], v[128:129], off
	global_load_dwordx4 v[144:147], v[128:129], off offset:256
	global_load_dwordx4 v[140:143], v[130:131], off
	global_load_dwordx4 v[136:139], v[130:131], off offset:256
	global_load_dwordx4 v[132:135], v[192:193], off
	s_nop 0
	global_load_dwordx4 v[128:131], v[192:193], off offset:256
	v_and_b32_e32 v192, 64, v191
	v_xor_b32_e32 v175, 16, v191
	v_add_u32_e32 v192, 64, v192
	v_xor_b32_e32 v193, 32, v191
	v_cmp_lt_i32_e32 vcc, v175, v192
	v_add_u32_e32 v218, 0x80, v174
	v_ashrrev_i32_e32 v219, 31, v218
	v_lshlrev_b64 v[218:219], 11, v[218:219]
	v_lshl_add_u64 v[218:219], v[176:177], 0, v[218:219]
	global_load_dwordx4 v[214:217], v[218:219], off
	global_load_dwordx4 v[218:221], v[218:219], off offset:256
	v_add_u32_e32 v226, 0x90, v174
	v_ashrrev_i32_e32 v227, 31, v226
	v_lshlrev_b64 v[226:227], 11, v[226:227]
	v_lshl_add_u64 v[226:227], v[176:177], 0, v[226:227]
	global_load_dwordx4 v[222:225], v[226:227], off
	global_load_dwordx4 v[226:229], v[226:227], off offset:256
	v_add_u32_e32 v234, 0xa0, v174
	v_ashrrev_i32_e32 v235, 31, v234
	v_lshlrev_b64 v[234:235], 11, v[234:235]
	v_lshl_add_u64 v[234:235], v[176:177], 0, v[234:235]
	global_load_dwordx4 v[230:233], v[234:235], off
	global_load_dwordx4 v[234:237], v[234:235], off offset:256
	v_add_u32_e32 v238, 0xb0, v174
	v_ashrrev_i32_e32 v239, 31, v238
	v_lshlrev_b64 v[238:239], 11, v[238:239]
	v_lshl_add_u64 v[238:239], v[176:177], 0, v[238:239]
	global_load_dwordx4 v[238:241], v[238:239], off
	s_waitcnt vmcnt(7)
	v_lshlrev_b32_e32 v206, 16, v194
	v_cndmask_b32_e32 v175, v191, v175, vcc
	v_cmp_lt_i32_e32 vcc, v193, v192
	v_and_b32_e32 v207, 0xffff0000, v194
	v_lshlrev_b32_e32 v194, 16, v195
	v_and_b32_e32 v195, 0xffff0000, v195
	v_lshlrev_b32_e32 v208, 16, v196
	v_and_b32_e32 v209, 0xffff0000, v196
	v_lshlrev_b32_e32 v196, 16, v197
	v_and_b32_e32 v197, 0xffff0000, v197
	v_lshlrev_b32_e32 v210, 16, v198
	v_and_b32_e32 v211, 0xffff0000, v198
	v_lshlrev_b32_e32 v198, 16, v199
	v_and_b32_e32 v199, 0xffff0000, v199
	v_cndmask_b32_e32 v193, v191, v193, vcc
	v_lshlrev_b32_e32 v212, 16, v200
	v_and_b32_e32 v213, 0xffff0000, v200
	v_lshlrev_b32_e32 v200, 16, v201
	v_and_b32_e32 v201, 0xffff0000, v201
	v_pk_add_f32 v[126:127], v[126:127], v[194:195]
	v_pk_add_f32 v[124:125], v[124:125], v[206:207]
	v_pk_add_f32 v[122:123], v[122:123], v[196:197]
	v_pk_add_f32 v[120:121], v[120:121], v[208:209]
	v_pk_add_f32 v[118:119], v[118:119], v[198:199]
	v_pk_add_f32 v[116:117], v[116:117], v[210:211]
	v_lshlrev_b32_e32 v192, 2, v175
	v_lshlrev_b32_e32 v175, 2, v193
	v_pk_add_f32 v[194:195], v[114:115], v[200:201]
	v_pk_add_f32 v[196:197], v[112:113], v[212:213]
	v_mul_f32_e32 v193, v125, v125
	v_mul_f32_e32 v198, v127, v127
	v_mul_f32_e32 v199, v121, v121
	v_mul_f32_e32 v200, v123, v123
	v_cvt_pk_bf16_f32 v114, v120, v121
	v_cvt_pk_bf16_f32 v115, v122, v123
	v_mul_f32_e32 v121, v117, v117
	v_mul_f32_e32 v123, v119, v119
	v_cvt_pk_bf16_f32 v112, v124, v125
	v_mul_f32_e32 v125, v197, v197
	v_fmac_f32_e32 v193, v124, v124
	v_fmac_f32_e32 v198, v126, v126
	v_fmac_f32_e32 v121, v116, v116
	v_fmac_f32_e32 v123, v118, v118
	v_cvt_pk_bf16_f32 v113, v126, v127
	v_mul_f32_e32 v127, v195, v195
	v_fmac_f32_e32 v199, v120, v120
	v_fmac_f32_e32 v125, v196, v196
	v_add_f32_e32 v120, v193, v198
	v_add_f32_e32 v121, v121, v123
	v_fmac_f32_e32 v200, v122, v122
	v_fmac_f32_e32 v127, v194, v194
	v_add_f32_e32 v120, v199, v120
	v_add_f32_e32 v121, v125, v121
	v_add_f32_e32 v120, v200, v120
	v_add_f32_e32 v121, v127, v121
	v_add_f32_e32 v122, v120, v121
	ds_bpermute_b32 v123, v192, v122
	v_lshl_add_u64 v[120:121], s[82:83], 0, v[204:205]
	v_lshl_add_u64 v[120:121], v[120:121], 0, v[202:203]
	global_store_dwordx4 v[120:121], v[112:115], off
	s_waitcnt lgkmcnt(0)
	s_nop 0
	v_add_f32_e32 v112, v122, v123
	ds_bpermute_b32 v113, v175, v112
	v_cvt_pk_bf16_f32 v114, v116, v117
	v_cvt_pk_bf16_f32 v115, v118, v119
	v_cvt_pk_bf16_f32 v116, v196, v197
	v_cvt_pk_bf16_f32 v117, v194, v195
	global_store_dwordx4 v[120:121], v[114:117], off offset:256
	s_and_saveexec_b64 s[26:27], s[4:5]
	s_cbranch_execz .LBB0_1891
	s_waitcnt lgkmcnt(0)
	v_add_f32_e32 v112, v112, v113
	ds_write_b32 v186, v112

.LBB0_1897:
	s_or_b64 exec, exec, s[26:27]
	v_add_u32_e32 v64, 0x80, v174
	s_waitcnt lgkmcnt(0)
	v_ashrrev_i32_e32 v65, 31, v64
	v_lshlrev_b64 v[102:103], 11, v[64:65]
	v_lshl_add_u64 v[64:65], v[176:177], 0, v[102:103]
	v_add_u32_e32 v64, 0x90, v174
	v_add_u32_e32 v66, 0xa0, v174
	v_add_u32_e32 v68, 0xb0, v174
	v_ashrrev_i32_e32 v65, 31, v64
	v_ashrrev_i32_e32 v67, 31, v66
	v_ashrrev_i32_e32 v69, 31, v68
	v_lshlrev_b64 v[92:93], 11, v[64:65]
	v_lshlrev_b64 v[90:91], 11, v[66:67]
	v_lshlrev_b64 v[88:89], 11, v[68:69]
	v_lshl_add_u64 v[64:65], v[176:177], 0, v[92:93]
	v_lshl_add_u64 v[66:67], v[176:177], 0, v[90:91]
	v_lshl_add_u64 v[104:105], v[176:177], 0, v[88:89]
	s_nop 0
	global_load_dwordx4 v[64:67], v[104:105], off offset:256
	s_waitcnt vmcnt(15)
	v_lshlrev_b32_e32 v104, 16, v214
	v_and_b32_e32 v105, 0xffff0000, v214
	v_lshlrev_b32_e32 v214, 16, v215
	v_and_b32_e32 v215, 0xffff0000, v215
	v_lshlrev_b32_e32 v106, 16, v216
	v_and_b32_e32 v107, 0xffff0000, v216
	v_lshlrev_b32_e32 v216, 16, v217
	v_and_b32_e32 v217, 0xffff0000, v217
	s_waitcnt vmcnt(14)
	v_lshlrev_b32_e32 v108, 16, v218
	v_and_b32_e32 v109, 0xffff0000, v218
	v_lshlrev_b32_e32 v218, 16, v219
	v_and_b32_e32 v219, 0xffff0000, v219
	v_lshlrev_b32_e32 v110, 16, v220
	v_and_b32_e32 v111, 0xffff0000, v220
	v_lshlrev_b32_e32 v220, 16, v221
	v_and_b32_e32 v221, 0xffff0000, v221
	v_pk_add_f32 v[62:63], v[62:63], v[214:215]
	v_pk_add_f32 v[60:61], v[60:61], v[104:105]
	v_pk_add_f32 v[58:59], v[58:59], v[216:217]
	v_pk_add_f32 v[56:57], v[56:57], v[106:107]
	v_pk_add_f32 v[54:55], v[54:55], v[218:219]
	v_pk_add_f32 v[52:53], v[52:53], v[108:109]
	v_pk_add_f32 v[214:215], v[50:51], v[220:221]
	v_pk_add_f32 v[216:217], v[48:49], v[110:111]
	v_mul_f32_e32 v218, v61, v61
	v_mul_f32_e32 v219, v63, v63
	v_mul_f32_e32 v220, v57, v57
	v_mul_f32_e32 v221, v59, v59
	v_cvt_pk_bf16_f32 v50, v56, v57
	v_cvt_pk_bf16_f32 v51, v58, v59
	v_mul_f32_e32 v57, v53, v53
	v_mul_f32_e32 v59, v55, v55
	v_cvt_pk_bf16_f32 v48, v60, v61
	v_mul_f32_e32 v61, v217, v217
	v_fmac_f32_e32 v218, v60, v60
	v_fmac_f32_e32 v219, v62, v62
	v_fmac_f32_e32 v57, v52, v52
	v_fmac_f32_e32 v59, v54, v54
	v_cvt_pk_bf16_f32 v49, v62, v63
	v_mul_f32_e32 v63, v215, v215
	v_fmac_f32_e32 v220, v56, v56
	v_fmac_f32_e32 v61, v216, v216
	v_add_f32_e32 v56, v218, v219
	v_add_f32_e32 v57, v57, v59
	v_fmac_f32_e32 v221, v58, v58
	v_fmac_f32_e32 v63, v214, v214
	v_add_f32_e32 v56, v220, v56
	v_add_f32_e32 v57, v61, v57
	v_add_f32_e32 v56, v221, v56
	v_add_f32_e32 v57, v63, v57
	v_add_f32_e32 v58, v56, v57
	ds_bpermute_b32 v59, v192, v58
	v_lshl_add_u64 v[56:57], s[82:83], 0, v[102:103]
	v_lshl_add_u64 v[56:57], v[172:173], 1, v[56:57]
	global_store_dwordx4 v[56:57], v[48:51], off
	s_waitcnt lgkmcnt(0)
	s_nop 0
	v_add_f32_e32 v48, v58, v59
	ds_bpermute_b32 v49, v175, v48
	v_cvt_pk_bf16_f32 v50, v52, v53
	v_cvt_pk_bf16_f32 v51, v54, v55
	v_cvt_pk_bf16_f32 v52, v216, v217
	v_cvt_pk_bf16_f32 v53, v214, v215
	global_store_dwordx4 v[56:57], v[50:53], off offset:256
	s_and_saveexec_b64 s[26:27], s[4:5]
	s_cbranch_execz .LBB0_1899
	s_waitcnt lgkmcnt(0)
	v_add_f32_e32 v48, v48, v49
	ds_write_b32 v186, v48 offset:2048
.LBB0_1899:
	s_or_b64 exec, exec, s[26:27]
	s_waitcnt vmcnt(15)
	v_lshlrev_b32_e32 v48, 16, v222
	s_waitcnt lgkmcnt(0)
	v_and_b32_e32 v49, 0xffff0000, v222
	v_lshlrev_b32_e32 v50, 16, v223
	v_and_b32_e32 v51, 0xffff0000, v223
	v_lshlrev_b32_e32 v52, 16, v224
	v_and_b32_e32 v53, 0xffff0000, v224
	v_lshlrev_b32_e32 v54, 16, v225
	v_and_b32_e32 v55, 0xffff0000, v225
	v_pk_add_f32 v[46:47], v[46:47], v[50:51]
	v_pk_add_f32 v[44:45], v[44:45], v[48:49]
	v_pk_add_f32 v[48:49], v[42:43], v[54:55]
	v_pk_add_f32 v[42:43], v[40:41], v[52:53]
	v_mul_f32_e32 v40, v45, v45
	v_mul_f32_e32 v41, v47, v47
	v_fmac_f32_e32 v40, v44, v44
	v_fmac_f32_e32 v41, v46, v46
	v_add_f32_e32 v40, v40, v41
	v_mul_f32_e32 v41, v43, v43
	v_fmac_f32_e32 v41, v42, v42
	v_add_f32_e32 v40, v41, v40
	v_mul_f32_e32 v41, v49, v49
	v_fmac_f32_e32 v41, v48, v48
	v_add_f32_e32 v52, v41, v40
	v_cvt_pk_bf16_f32 v40, v44, v45
	v_cvt_pk_bf16_f32 v41, v46, v47
	s_waitcnt vmcnt(14)
	v_lshlrev_b32_e32 v44, 16, v226
	v_and_b32_e32 v45, 0xffff0000, v226
	v_lshlrev_b32_e32 v46, 16, v227
	v_and_b32_e32 v47, 0xffff0000, v227
	v_cvt_pk_bf16_f32 v42, v42, v43
	v_cvt_pk_bf16_f32 v43, v48, v49
	v_lshlrev_b32_e32 v48, 16, v228
	v_and_b32_e32 v49, 0xffff0000, v228
	v_pk_add_f32 v[38:39], v[38:39], v[46:47]
	v_pk_add_f32 v[36:37], v[36:37], v[44:45]
	v_pk_add_f32 v[46:47], v[32:33], v[48:49]
	v_mul_f32_e32 v32, v37, v37
	v_mul_f32_e32 v33, v39, v39
	v_fmac_f32_e32 v32, v36, v36
	v_fmac_f32_e32 v33, v38, v38
	v_lshlrev_b32_e32 v50, 16, v229
	v_and_b32_e32 v51, 0xffff0000, v229
	v_add_f32_e32 v32, v32, v33
	v_mul_f32_e32 v33, v47, v47
	v_pk_add_f32 v[44:45], v[34:35], v[50:51]
	v_fmac_f32_e32 v33, v46, v46
	v_add_f32_e32 v32, v33, v32
	v_mul_f32_e32 v33, v45, v45
	v_fmac_f32_e32 v33, v44, v44
	v_add_f32_e32 v32, v33, v32
	v_add_f32_e32 v35, v52, v32
	ds_bpermute_b32 v50, v192, v35
	v_lshl_add_u64 v[32:33], s[82:83], 0, v[92:93]
	v_lshl_add_u64 v[48:49], v[172:173], 1, v[32:33]
	v_cvt_pk_bf16_f32 v34, v36, v37
	v_cvt_pk_bf16_f32 v36, v46, v47
	s_waitcnt lgkmcnt(0)
	v_add_f32_e32 v32, v35, v50
	ds_bpermute_b32 v33, v175, v32
	v_cvt_pk_bf16_f32 v35, v38, v39
	v_cvt_pk_bf16_f32 v37, v44, v45
	global_store_dwordx4 v[48:49], v[40:43], off
	global_store_dwordx4 v[48:49], v[34:37], off offset:256
	s_and_saveexec_b64 s[26:27], s[4:5]
	s_cbranch_execz .LBB0_1901
	s_waitcnt lgkmcnt(0)
	v_add_f32_e32 v32, v32, v33
	ds_write_b32 v186, v32 offset:2304
.LBB0_1901:
	s_or_b64 exec, exec, s[26:27]
	s_waitcnt vmcnt(15)
	v_lshlrev_b32_e32 v32, 16, v230
	s_waitcnt lgkmcnt(0)
	v_and_b32_e32 v33, 0xffff0000, v230
	v_lshlrev_b32_e32 v34, 16, v231
	v_and_b32_e32 v35, 0xffff0000, v231
	v_lshlrev_b32_e32 v36, 16, v232
	v_and_b32_e32 v37, 0xffff0000, v232
	v_lshlrev_b32_e32 v38, 16, v233
	v_and_b32_e32 v39, 0xffff0000, v233
	v_pk_add_f32 v[30:31], v[30:31], v[34:35]
	v_pk_add_f32 v[28:29], v[28:29], v[32:33]
	v_pk_add_f32 v[32:33], v[26:27], v[38:39]
	v_pk_add_f32 v[26:27], v[24:25], v[36:37]
	v_mul_f32_e32 v24, v29, v29
	v_mul_f32_e32 v25, v31, v31
	v_fmac_f32_e32 v24, v28, v28
	v_fmac_f32_e32 v25, v30, v30
	v_add_f32_e32 v24, v24, v25
	v_mul_f32_e32 v25, v27, v27
	v_fmac_f32_e32 v25, v26, v26
	v_add_f32_e32 v24, v25, v24
	v_mul_f32_e32 v25, v33, v33
	v_fmac_f32_e32 v25, v32, v32
	v_add_f32_e32 v36, v25, v24
	v_cvt_pk_bf16_f32 v24, v28, v29
	v_cvt_pk_bf16_f32 v25, v30, v31
	s_waitcnt vmcnt(14)
	v_lshlrev_b32_e32 v28, 16, v234
	v_and_b32_e32 v29, 0xffff0000, v234
	v_lshlrev_b32_e32 v30, 16, v235
	v_and_b32_e32 v31, 0xffff0000, v235
	v_cvt_pk_bf16_f32 v26, v26, v27
	v_cvt_pk_bf16_f32 v27, v32, v33
	v_lshlrev_b32_e32 v32, 16, v236
	v_and_b32_e32 v33, 0xffff0000, v236
	v_pk_add_f32 v[22:23], v[22:23], v[30:31]
	v_pk_add_f32 v[20:21], v[20:21], v[28:29]
	v_pk_add_f32 v[30:31], v[16:17], v[32:33]
	v_mul_f32_e32 v16, v21, v21
	v_mul_f32_e32 v17, v23, v23
	v_fmac_f32_e32 v16, v20, v20
	v_fmac_f32_e32 v17, v22, v22
	v_lshlrev_b32_e32 v34, 16, v237
	v_and_b32_e32 v35, 0xffff0000, v237
	v_add_f32_e32 v16, v16, v17
	v_mul_f32_e32 v17, v31, v31
	v_pk_add_f32 v[28:29], v[18:19], v[34:35]
	v_fmac_f32_e32 v17, v30, v30
	v_add_f32_e32 v16, v17, v16
	v_mul_f32_e32 v17, v29, v29
	v_fmac_f32_e32 v17, v28, v28
	v_add_f32_e32 v16, v17, v16
	v_add_f32_e32 v19, v36, v16
	ds_bpermute_b32 v34, v192, v19
	v_lshl_add_u64 v[16:17], s[82:83], 0, v[90:91]
	v_lshl_add_u64 v[32:33], v[172:173], 1, v[16:17]
	v_cvt_pk_bf16_f32 v18, v20, v21
	v_cvt_pk_bf16_f32 v20, v30, v31
	s_waitcnt lgkmcnt(0)
	v_add_f32_e32 v16, v19, v34
	ds_bpermute_b32 v17, v175, v16
	v_cvt_pk_bf16_f32 v19, v22, v23
	v_cvt_pk_bf16_f32 v21, v28, v29
	global_store_dwordx4 v[32:33], v[24:27], off
	global_store_dwordx4 v[32:33], v[18:21], off offset:256
	s_and_saveexec_b64 s[26:27], s[4:5]
	s_cbranch_execz .LBB0_1903
	s_waitcnt lgkmcnt(0)
	v_add_f32_e32 v16, v16, v17
	ds_write_b32 v186, v16 offset:2560
.LBB0_1903:
	s_or_b64 exec, exec, s[26:27]
	s_waitcnt vmcnt(15)
	v_lshlrev_b32_e32 v16, 16, v238
	s_waitcnt lgkmcnt(0)
	v_and_b32_e32 v17, 0xffff0000, v238
	v_lshlrev_b32_e32 v18, 16, v239
	v_and_b32_e32 v19, 0xffff0000, v239
	v_lshlrev_b32_e32 v20, 16, v240
	v_and_b32_e32 v21, 0xffff0000, v240
	v_lshlrev_b32_e32 v22, 16, v241
	v_and_b32_e32 v23, 0xffff0000, v241
	v_pk_add_f32 v[14:15], v[14:15], v[18:19]
	v_pk_add_f32 v[12:13], v[12:13], v[16:17]
	v_pk_add_f32 v[16:17], v[10:11], v[22:23]
	v_pk_add_f32 v[10:11], v[8:9], v[20:21]
	v_mul_f32_e32 v8, v13, v13
	v_mul_f32_e32 v9, v15, v15
	v_fmac_f32_e32 v8, v12, v12
	v_fmac_f32_e32 v9, v14, v14
	v_add_f32_e32 v8, v8, v9
	v_mul_f32_e32 v9, v11, v11
	v_fmac_f32_e32 v9, v10, v10
	v_add_f32_e32 v8, v9, v8
	v_mul_f32_e32 v9, v17, v17
	v_fmac_f32_e32 v9, v16, v16
	v_add_f32_e32 v20, v9, v8
	v_cvt_pk_bf16_f32 v8, v12, v13
	v_cvt_pk_bf16_f32 v9, v14, v15
	s_waitcnt vmcnt(6)
	v_lshlrev_b32_e32 v12, 16, v64
	v_and_b32_e32 v13, 0xffff0000, v64
	v_lshlrev_b32_e32 v14, 16, v65
	v_and_b32_e32 v15, 0xffff0000, v65
	v_cvt_pk_bf16_f32 v10, v10, v11
	v_cvt_pk_bf16_f32 v11, v16, v17
	v_lshlrev_b32_e32 v16, 16, v66
	v_and_b32_e32 v17, 0xffff0000, v66
	v_pk_add_f32 v[6:7], v[6:7], v[14:15]
	v_pk_add_f32 v[4:5], v[4:5], v[12:13]
	v_pk_add_f32 v[14:15], v[0:1], v[16:17]
	v_mul_f32_e32 v0, v5, v5
	v_mul_f32_e32 v1, v7, v7
	v_fmac_f32_e32 v0, v4, v4
	v_fmac_f32_e32 v1, v6, v6
	v_lshlrev_b32_e32 v18, 16, v67
	v_and_b32_e32 v19, 0xffff0000, v67
	v_add_f32_e32 v0, v0, v1
	v_mul_f32_e32 v1, v15, v15
	v_pk_add_f32 v[12:13], v[2:3], v[18:19]
	v_fmac_f32_e32 v1, v14, v14
	v_add_f32_e32 v0, v1, v0
	v_mul_f32_e32 v1, v13, v13
	v_fmac_f32_e32 v1, v12, v12
	v_add_f32_e32 v0, v1, v0
	v_add_f32_e32 v3, v20, v0
	ds_bpermute_b32 v18, v192, v3
	v_lshl_add_u64 v[0:1], s[82:83], 0, v[88:89]
	v_lshl_add_u64 v[16:17], v[172:173], 1, v[0:1]
	v_cvt_pk_bf16_f32 v2, v4, v5
	v_cvt_pk_bf16_f32 v4, v14, v15
	s_waitcnt lgkmcnt(0)
	v_add_f32_e32 v0, v3, v18
	ds_bpermute_b32 v1, v175, v0
	v_cvt_pk_bf16_f32 v3, v6, v7
	v_cvt_pk_bf16_f32 v5, v12, v13
	global_store_dwordx4 v[16:17], v[8:11], off
	global_store_dwordx4 v[16:17], v[2:5], off offset:256
	s_and_saveexec_b64 s[26:27], s[4:5]
	s_cbranch_execz .LBB0_1905
	s_waitcnt lgkmcnt(0)
	v_add_f32_e32 v0, v0, v1
	ds_write_b32 v186, v0 offset:2816
